# gdn_g1 forward substitution LDS prefetch pool deepened to 12 groups (11 reads ahead) instead of 8
# baseline (speedup 1.0000x reference)
; DI void gdn_g1(const Params& p, int l, int ch, char* smem) {
;     ...
;     sA[c * 64 + s] = a; }
;   __syncthreads();
;   { const float f2 = bc * expf(Gc);
; #pragma unroll
;     for (int d = 0; d < 16; ++d) { sR[c * 129 + part * 16 + d] *= bc; sR[c * 129 + 64 + part * 16 + d] *= f2; } }
;   __syncthreads();
;   if (tid < 128) {
;     float sol[64];
; #pragma unroll
;     for (int cc = 0; cc < 64; ++cc) sol[cc] = sR[cc * 129 + tid];
; #pragma unroll
;     for (int cc = 1; cc < 64; ++cc) { float a0 = 0.f, a1 = 0.f;
; #pragma unroll
;       for (int s2 = 0; s2 < cc; ++s2) { if (s2 & 1) a1 += sA[cc * 64 + s2] * sol[s2]; else a0 += sA[cc * 64 + s2] * sol[s2]; }
.LBB0_660:
	s_or_b64 exec, exec, s[8:9]
	v_mul_f32_e32 v5, 0x3fb8aa3b, v2
	ds_write_b32 v6, v8 offset:240
	v_rndne_f32_e32 v6, v5
	s_mov_b32 s2, 0x3fb8aa3b
	v_sub_f32_e32 v7, v5, v6
	v_fma_f32 v5, v2, s2, -v5
	v_fmac_f32_e32 v5, 0x32a5705f, v2
	v_add_f32_e32 v5, v7, v5
	v_exp_f32_e32 v5, v5
	v_cvt_i32_f32_e32 v6, v6
	v_add_u32_e32 v71, 0x4000, v4
	s_waitcnt lgkmcnt(0)
	s_barrier
	v_ldexp_f32 v5, v5, v6
	ds_read2_b32 v[6:7], v71 offset1:1
	v_mov_b32_e32 v8, v3
	s_mov_b32 s2, 0xc2ce8ed0
	v_cmp_ngt_f32_e32 vcc, s2, v2
	s_mov_b32 s2, 0x42b17218
	s_waitcnt lgkmcnt(0)
	v_pk_mul_f32 v[6:7], v[8:9], v[6:7] op_sel_hi:[0,1]
	ds_write2_b32 v71, v6, v7 offset1:1
	ds_read2_b32 v[6:7], v65 offset1:1
	v_cndmask_b32_e32 v5, 0, v5, vcc
	v_cmp_nlt_f32_e32 vcc, s2, v2
	v_add_u32_e32 v72, 0x4008, v4
	v_add_u32_e32 v73, 0x4010, v4
	v_cndmask_b32_e32 v2, v187, v5, vcc
	v_mul_f32_e32 v2, v3, v2
	s_waitcnt lgkmcnt(0)
	v_pk_mul_f32 v[6:7], v[2:3], v[6:7] op_sel_hi:[0,1]
	ds_write2_b32 v65, v6, v7 offset1:1
	ds_read2_b32 v[6:7], v72 offset1:1
	v_add_u32_e32 v74, 0x4018, v4
	v_add_u32_e32 v78, 0x4038, v4
	v_add_u32_e32 v75, 0x4020, v4
	v_add_u32_e32 v76, 0x4028, v4
	s_waitcnt lgkmcnt(0)
	v_pk_mul_f32 v[6:7], v[8:9], v[6:7] op_sel_hi:[0,1]
	ds_write2_b32 v72, v6, v7 offset1:1
	ds_read2_b32 v[6:7], v66 offset1:1
	v_add_u32_e32 v77, 0x4030, v4
	s_movk_i32 s2, 0x80
	v_cmp_gt_i32_e32 vcc, s2, v89
	ds_read2_b32 v[4:5], v78 offset1:1
	s_waitcnt lgkmcnt(1)
	v_pk_mul_f32 v[6:7], v[2:3], v[6:7] op_sel_hi:[0,1]
	ds_write2_b32 v66, v6, v7 offset1:1
	ds_read2_b32 v[6:7], v73 offset1:1
	s_waitcnt lgkmcnt(2)
	v_pk_mul_f32 v[4:5], v[8:9], v[4:5] op_sel_hi:[0,1]
	ds_write2_b32 v78, v4, v5 offset1:1
	ds_read2_b32 v[4:5], v63 offset1:1
	s_waitcnt lgkmcnt(2)
	v_pk_mul_f32 v[6:7], v[8:9], v[6:7] op_sel_hi:[0,1]
	ds_write2_b32 v73, v6, v7 offset1:1
	ds_read2_b32 v[6:7], v70 offset1:1
	s_waitcnt lgkmcnt(0)
	v_pk_mul_f32 v[6:7], v[2:3], v[6:7] op_sel_hi:[0,1]
	ds_write2_b32 v70, v6, v7 offset1:1
	ds_read2_b32 v[6:7], v74 offset1:1
	s_waitcnt lgkmcnt(0)
	v_pk_mul_f32 v[6:7], v[8:9], v[6:7] op_sel_hi:[0,1]
	ds_write2_b32 v74, v6, v7 offset1:1
	ds_read2_b32 v[6:7], v64 offset1:1
	s_waitcnt lgkmcnt(0)
	v_pk_mul_f32 v[6:7], v[2:3], v[6:7] op_sel_hi:[0,1]
	ds_write2_b32 v64, v6, v7 offset1:1
	ds_read2_b32 v[6:7], v75 offset1:1
	s_waitcnt lgkmcnt(0)
	v_pk_mul_f32 v[6:7], v[8:9], v[6:7] op_sel_hi:[0,1]
	ds_write2_b32 v75, v6, v7 offset1:1
	ds_read2_b32 v[6:7], v67 offset1:1
	s_waitcnt lgkmcnt(0)
	v_pk_mul_f32 v[6:7], v[2:3], v[6:7] op_sel_hi:[0,1]
	ds_write2_b32 v67, v6, v7 offset1:1
	ds_read2_b32 v[6:7], v76 offset1:1
	s_waitcnt lgkmcnt(0)
	v_pk_mul_f32 v[6:7], v[8:9], v[6:7] op_sel_hi:[0,1]
	ds_write2_b32 v76, v6, v7 offset1:1
	ds_read2_b32 v[6:7], v69 offset1:1
	s_waitcnt lgkmcnt(0)
	v_pk_mul_f32 v[6:7], v[2:3], v[6:7] op_sel_hi:[0,1]
	ds_write2_b32 v69, v6, v7 offset1:1
	ds_read2_b32 v[6:7], v77 offset1:1
	s_waitcnt lgkmcnt(0)
	v_pk_mul_f32 v[6:7], v[8:9], v[6:7] op_sel_hi:[0,1]
	ds_write2_b32 v77, v6, v7 offset1:1
	ds_read2_b32 v[6:7], v68 offset1:1
	s_waitcnt lgkmcnt(0)
	v_pk_mul_f32 v[6:7], v[2:3], v[6:7] op_sel_hi:[0,1]
	v_pk_mul_f32 v[2:3], v[2:3], v[4:5] op_sel_hi:[0,1]
	ds_write2_b32 v68, v6, v7 offset1:1
	ds_write2_b32 v63, v2, v3 offset1:1
	s_waitcnt lgkmcnt(0)
	s_barrier
	s_and_saveexec_b64 s[44:45], vcc
	s_cbranch_execz .LBB0_662
	v_lshlrev_b32_e32 v79, 2, v89
	v_add_u32_e32 v2, 0x4000, v79
	ds_read2_b32 v[4:5], v2 offset1:129
	v_add_u32_e32 v2, 0x4400, v79
	ds_read2_b32 v[80:81], v2 offset0:2 offset1:131
	v_add_u32_e32 v2, 0x4800, v79
	ds_read2_b32 v[90:91], v2 offset0:4 offset1:133
	v_add_u32_e32 v2, 0x4c00, v79
	ds_read2_b32 v[60:61], v2 offset0:6 offset1:135
	v_add_u32_e32 v2, 0x5000, v79
	ds_read2_b32 v[58:59], v2 offset0:8 offset1:137
	v_add_u32_e32 v2, 0x5400, v79
	ds_read2_b32 v[56:57], v2 offset0:10 offset1:139
	v_add_u32_e32 v2, 0x5800, v79
	ds_read2_b32 v[54:55], v2 offset0:12 offset1:141
	v_add_u32_e32 v2, 0x5c00, v79
	ds_read2_b32 v[52:53], v2 offset0:14 offset1:143
	v_add_u32_e32 v2, 0x6000, v79
	ds_read2_b32 v[50:51], v2 offset0:16 offset1:145
	v_add_u32_e32 v2, 0x6400, v79
	ds_read2_b32 v[48:49], v2 offset0:18 offset1:147
	v_add_u32_e32 v2, 0x6800, v79
	ds_read2_b32 v[46:47], v2 offset0:20 offset1:149
	v_add_u32_e32 v2, 0x6c00, v79
	ds_read2_b32 v[44:45], v2 offset0:22 offset1:151
	v_add_u32_e32 v2, 0x7000, v79
	ds_read2_b32 v[42:43], v2 offset0:24 offset1:153
	v_add_u32_e32 v2, 0x7400, v79
	ds_read2_b32 v[40:41], v2 offset0:26 offset1:155
	v_add_u32_e32 v2, 0x7800, v79
	ds_read2_b32 v[38:39], v2 offset0:28 offset1:157
	v_add_u32_e32 v2, 0x7c00, v79
	ds_read2_b32 v[36:37], v2 offset0:30 offset1:159
	v_add_u32_e32 v2, 0x8000, v79
	ds_read2_b32 v[34:35], v2 offset0:32 offset1:161
	v_add_u32_e32 v2, 0x8400, v79
	ds_read2_b32 v[32:33], v2 offset0:34 offset1:163
	v_add_u32_e32 v2, 0x8800, v79
	ds_read2_b32 v[30:31], v2 offset0:36 offset1:165
	v_add_u32_e32 v2, 0x8c00, v79
	ds_read2_b32 v[28:29], v2 offset0:38 offset1:167
	v_add_u32_e32 v2, 0x9000, v79
	ds_read2_b32 v[26:27], v2 offset0:40 offset1:169
	v_add_u32_e32 v2, 0x9400, v79
	ds_read2_b32 v[24:25], v2 offset0:42 offset1:171
	v_add_u32_e32 v2, 0x9800, v79
	ds_read2_b32 v[22:23], v2 offset0:44 offset1:173
	v_add_u32_e32 v2, 0x9c00, v79
	ds_read2_b32 v[20:21], v2 offset0:46 offset1:175
	v_add_u32_e32 v2, 0xa000, v79
	ds_read2_b32 v[18:19], v2 offset0:48 offset1:177
	v_add_u32_e32 v2, 0xa400, v79
	ds_read2_b32 v[16:17], v2 offset0:50 offset1:179
	v_add_u32_e32 v2, 0xa800, v79
	ds_read2_b32 v[14:15], v2 offset0:52 offset1:181
	v_add_u32_e32 v2, 0xac00, v79
	ds_read2_b32 v[12:13], v2 offset0:54 offset1:183
	v_add_u32_e32 v2, 0xb000, v79
	ds_read2_b32 v[10:11], v2 offset0:56 offset1:185
	v_add_u32_e32 v2, 0xb400, v79
	ds_read2_b32 v[8:9], v2 offset0:58 offset1:187
	v_add_u32_e32 v2, 0xb800, v79
	ds_read2_b32 v[6:7], v2 offset0:60 offset1:189
	v_add_u32_e32 v2, 0xbc00, v79
	ds_read2_b32 v[2:3], v2 offset0:62 offset1:191
	ds_read_b32 v82, v143 offset:256
	s_waitcnt lgkmcnt(0)
; DI void gdn_g1(const Params& p, int l, int ch, char* smem) {
;     ...
;     for (int cc = 1; cc < 64; ++cc) { float a0 = 0.f, a1 = 0.f;
; #pragma unroll
;       for (int s2 = 0; s2 < cc; ++s2) { if (s2 & 1) a1 += sA[cc * 64 + s2] * sol[s2]; else a0 += sA[cc * 64 + s2] * sol[s2]; }
;       sol[cc] -= a0 + a1; }
	v_fma_f32 v82, v4, v82, 0
	v_sub_f32_e32 v5, v5, v82
	ds_read_b64 v[82:83], v143 offset:512
	s_waitcnt lgkmcnt(0)
	v_fma_f32 v82, v4, v82, 0
	v_fma_f32 v83, v83, v5, 0
	v_add_f32_e32 v82, v82, v83
	v_sub_f32_e32 v80, v80, v82
	ds_read_b96 v[82:84], v143 offset:768
	s_waitcnt lgkmcnt(0)
	v_fma_f32 v82, v4, v82, 0
	v_fma_f32 v83, v5, v83, 0
	v_fmac_f32_e32 v82, v84, v80
	v_add_f32_e32 v82, v83, v82
	v_sub_f32_e32 v81, v81, v82
	ds_read_b128 v[82:85], v143 offset:1024
	s_waitcnt lgkmcnt(0)
	v_fma_f32 v82, v4, v82, 0
	v_fma_f32 v83, v5, v83, 0
	v_fmac_f32_e32 v82, v80, v84
	v_fmac_f32_e32 v83, v85, v81
	ds_read_b128 v[114:117], v143 offset:1280
	ds_read_b32 v119, v143 offset:1296
	ds_read_b128 v[122:125], v143 offset:1536
	ds_read_b64 v[126:127], v143 offset:1552
	ds_read_b128 v[130:133], v143 offset:1792
	ds_read_b96 v[134:136], v143 offset:1808
	ds_read_b128 v[146:149], v143 offset:2048
	ds_read_b128 v[150:153], v143 offset:2064
	ds_read_b128 v[154:157], v143 offset:2304
	ds_read_b128 v[158:161], v143 offset:2320
	ds_read_b32 v162, v143 offset:2336
	ds_read_b128 v[166:169], v143 offset:2560
	v_add_f32_e32 v82, v82, v83
	v_sub_f32_e32 v82, v90, v82
	s_waitcnt lgkmcnt(11)
	v_fma_f32 v83, v4, v114, 0
	v_fma_f32 v84, v5, v115, 0
	v_fmac_f32_e32 v83, v80, v116
	v_fmac_f32_e32 v84, v81, v117
	ds_read_b128 v[114:117], v143 offset:2576
	s_waitcnt lgkmcnt(11)
	v_fmac_f32_e32 v83, v119, v82
	v_add_f32_e32 v83, v84, v83
	ds_read_b64 v[118:119], v143 offset:2592
	v_sub_f32_e32 v83, v91, v83
	s_waitcnt lgkmcnt(11)
	v_fma_f32 v88, v4, v122, 0
	v_fma_f32 v90, v5, v123, 0
	v_fmac_f32_e32 v88, v80, v124
	v_fmac_f32_e32 v90, v81, v125
	ds_read_b128 v[122:125], v143 offset:2816
	s_waitcnt lgkmcnt(11)
	v_fmac_f32_e32 v88, v82, v126
	v_fmac_f32_e32 v90, v83, v127
	v_add_f32_e32 v84, v88, v90
	v_sub_f32_e32 v60, v60, v84
	ds_read_b128 v[126:129], v143 offset:2832
	s_waitcnt lgkmcnt(11)
	v_fma_f32 v88, v4, v130, 0
	v_fma_f32 v90, v5, v131, 0
	v_fmac_f32_e32 v88, v80, v132
	v_fmac_f32_e32 v90, v81, v133
	ds_read_b96 v[130:132], v143 offset:2848
	s_waitcnt lgkmcnt(11)
	v_fmac_f32_e32 v88, v82, v134
	v_fmac_f32_e32 v90, v83, v135
	v_fmac_f32_e32 v88, v60, v136
	v_add_f32_e32 v84, v90, v88
	v_sub_f32_e32 v61, v61, v84
	ds_read_b128 v[134:137], v143 offset:3072
	s_waitcnt lgkmcnt(11)
	v_fma_f32 v88, v4, v146, 0
	v_fma_f32 v90, v5, v147, 0
	v_fmac_f32_e32 v88, v80, v148
	v_fmac_f32_e32 v90, v81, v149
	ds_read_b128 v[146:149], v143 offset:3088
	s_waitcnt lgkmcnt(11)
	v_fmac_f32_e32 v88, v82, v150
	v_fmac_f32_e32 v90, v83, v151
	v_fmac_f32_e32 v88, v60, v152
	v_fmac_f32_e32 v90, v61, v153
	v_add_f32_e32 v84, v88, v90
	v_sub_f32_e32 v58, v58, v84
	ds_read_b128 v[150:153], v143 offset:3104
	s_waitcnt lgkmcnt(11)
	v_fma_f32 v88, v4, v154, 0
	v_fma_f32 v90, v5, v155, 0
	v_fmac_f32_e32 v88, v80, v156
	v_fmac_f32_e32 v90, v81, v157
	ds_read_b128 v[154:157], v143 offset:3328
	s_waitcnt lgkmcnt(11)
	v_fmac_f32_e32 v88, v82, v158
	v_fmac_f32_e32 v90, v83, v159
	v_fmac_f32_e32 v88, v60, v160
	v_fmac_f32_e32 v90, v61, v161
	ds_read_b128 v[158:161], v143 offset:3344
	s_waitcnt lgkmcnt(11)
	v_fmac_f32_e32 v88, v58, v162
	v_add_f32_e32 v84, v90, v88
	v_sub_f32_e32 v59, v59, v84
	ds_read_b128 v[162:165], v143 offset:3360
	s_waitcnt lgkmcnt(11)
	v_fma_f32 v88, v4, v166, 0
	v_fma_f32 v90, v5, v167, 0
	v_fmac_f32_e32 v88, v80, v168
	v_fmac_f32_e32 v90, v81, v169
	ds_read_b32 v166, v143 offset:3376
	s_waitcnt lgkmcnt(11)
	v_fmac_f32_e32 v88, v82, v114
	v_fmac_f32_e32 v90, v83, v115
	v_fmac_f32_e32 v88, v60, v116
	v_fmac_f32_e32 v90, v61, v117
	ds_read_b128 v[114:117], v143 offset:3584
	s_waitcnt lgkmcnt(11)
	v_fmac_f32_e32 v88, v58, v118
	v_fmac_f32_e32 v90, v59, v119
	v_add_f32_e32 v84, v88, v90
	v_sub_f32_e32 v56, v56, v84
	ds_read_b128 v[118:121], v143 offset:3600
	s_waitcnt lgkmcnt(11)
	v_fma_f32 v88, v4, v122, 0
	v_fma_f32 v90, v5, v123, 0
	v_fmac_f32_e32 v88, v80, v124
	v_fmac_f32_e32 v90, v81, v125
	ds_read_b128 v[122:125], v143 offset:3616
	s_waitcnt lgkmcnt(11)
	v_fmac_f32_e32 v88, v82, v126
	v_fmac_f32_e32 v90, v83, v127
	v_fmac_f32_e32 v88, v60, v128
	v_fmac_f32_e32 v90, v61, v129
	ds_read_b64 v[126:127], v143 offset:3632
	s_waitcnt lgkmcnt(11)
	v_fmac_f32_e32 v88, v58, v130
	v_fmac_f32_e32 v90, v59, v131
	v_fmac_f32_e32 v88, v56, v132
	v_add_f32_e32 v84, v90, v88
	v_sub_f32_e32 v57, v57, v84
	ds_read_b128 v[130:133], v143 offset:3840
	s_waitcnt lgkmcnt(11)
	v_fma_f32 v88, v4, v134, 0
	v_fma_f32 v90, v5, v135, 0
	v_fmac_f32_e32 v88, v80, v136
	v_fmac_f32_e32 v90, v81, v137
	ds_read_b128 v[134:137], v143 offset:3856
	s_waitcnt lgkmcnt(11)
	v_fmac_f32_e32 v88, v82, v146
	v_fmac_f32_e32 v90, v83, v147
	v_fmac_f32_e32 v88, v60, v148
	v_fmac_f32_e32 v90, v61, v149
	ds_read_b128 v[146:149], v143 offset:3872
	s_waitcnt lgkmcnt(11)
	v_fmac_f32_e32 v88, v58, v150
	v_fmac_f32_e32 v90, v59, v151
	v_fmac_f32_e32 v88, v56, v152
	v_fmac_f32_e32 v90, v57, v153
	v_add_f32_e32 v84, v88, v90
	v_sub_f32_e32 v54, v54, v84
	ds_read_b96 v[150:152], v143 offset:3888
	s_waitcnt lgkmcnt(11)
	v_fma_f32 v88, v4, v154, 0
	v_fma_f32 v90, v5, v155, 0
	v_fmac_f32_e32 v88, v80, v156
	v_fmac_f32_e32 v90, v81, v157
	ds_read_b128 v[154:157], v143 offset:4096
	s_waitcnt lgkmcnt(11)
	v_fmac_f32_e32 v88, v82, v158
	v_fmac_f32_e32 v90, v83, v159
	v_fmac_f32_e32 v88, v60, v160
	v_fmac_f32_e32 v90, v61, v161
	ds_read_b128 v[158:161], v143 offset:4112
	s_waitcnt lgkmcnt(11)
	v_fmac_f32_e32 v88, v58, v162
	v_fmac_f32_e32 v90, v59, v163
	v_fmac_f32_e32 v88, v56, v164
	v_fmac_f32_e32 v90, v57, v165
	ds_read_b128 v[162:165], v143 offset:4128
	s_waitcnt lgkmcnt(11)
; DI void gdn_g1(const Params& p, int l, int ch, char* smem) {
;     ...
;     for (int cc = 1; cc < 64; ++cc) { float a0 = 0.f, a1 = 0.f;
; #pragma unroll
;       for (int s2 = 0; s2 < cc; ++s2) { if (s2 & 1) a1 += sA[cc * 64 + s2] * sol[s2]; else a0 += sA[cc * 64 + s2] * sol[s2]; }
;       sol[cc] -= a0 + a1; }
	v_fmac_f32_e32 v88, v54, v166
	v_add_f32_e32 v84, v90, v88
	v_sub_f32_e32 v55, v55, v84
	ds_read_b128 v[166:169], v143 offset:4144
	s_waitcnt lgkmcnt(11)
	v_fma_f32 v88, v4, v114, 0
	v_fma_f32 v90, v5, v115, 0
	v_fmac_f32_e32 v88, v80, v116
	v_fmac_f32_e32 v90, v81, v117
	ds_read_b128 v[114:117], v143 offset:4352
	s_waitcnt lgkmcnt(11)
	v_fmac_f32_e32 v88, v82, v118
	v_fmac_f32_e32 v90, v83, v119
	v_fmac_f32_e32 v88, v60, v120
	v_fmac_f32_e32 v90, v61, v121
	ds_read_b128 v[118:121], v143 offset:4368
	s_waitcnt lgkmcnt(11)
	v_fmac_f32_e32 v88, v58, v122
	v_fmac_f32_e32 v90, v59, v123
	v_fmac_f32_e32 v88, v56, v124
	v_fmac_f32_e32 v90, v57, v125
	ds_read_b128 v[122:125], v143 offset:4384
	s_waitcnt lgkmcnt(11)
	v_fmac_f32_e32 v88, v54, v126
	v_fmac_f32_e32 v90, v55, v127
	v_add_f32_e32 v84, v88, v90
	v_sub_f32_e32 v52, v52, v84
	ds_read_b128 v[126:129], v143 offset:4400
	s_waitcnt lgkmcnt(11)
	v_fma_f32 v88, v4, v130, 0
	v_fma_f32 v90, v5, v131, 0
	v_fmac_f32_e32 v88, v80, v132
	v_fmac_f32_e32 v90, v81, v133
	ds_read_b32 v130, v143 offset:4416
	s_waitcnt lgkmcnt(11)
	v_fmac_f32_e32 v88, v82, v134
	v_fmac_f32_e32 v90, v83, v135
	v_fmac_f32_e32 v88, v60, v136
	v_fmac_f32_e32 v90, v61, v137
	ds_read_b128 v[134:137], v143 offset:4608
	s_waitcnt lgkmcnt(11)
	v_fmac_f32_e32 v88, v58, v146
	v_fmac_f32_e32 v90, v59, v147
	v_fmac_f32_e32 v88, v56, v148
	v_fmac_f32_e32 v90, v57, v149
	ds_read_b128 v[146:149], v143 offset:4624
	s_waitcnt lgkmcnt(11)
	v_fmac_f32_e32 v88, v54, v150
	v_fmac_f32_e32 v90, v55, v151
	v_fmac_f32_e32 v88, v52, v152
	v_add_f32_e32 v84, v90, v88
	v_sub_f32_e32 v53, v53, v84
	ds_read_b128 v[150:153], v143 offset:4640
	s_waitcnt lgkmcnt(11)
	v_fma_f32 v88, v4, v154, 0
	v_fma_f32 v90, v5, v155, 0
	v_fmac_f32_e32 v88, v80, v156
	v_fmac_f32_e32 v90, v81, v157
	ds_read_b128 v[154:157], v143 offset:4656
	s_waitcnt lgkmcnt(11)
	v_fmac_f32_e32 v88, v82, v158
	v_fmac_f32_e32 v90, v83, v159
	v_fmac_f32_e32 v88, v60, v160
	v_fmac_f32_e32 v90, v61, v161
	ds_read_b64 v[158:159], v143 offset:4672
	s_waitcnt lgkmcnt(11)
	v_fmac_f32_e32 v88, v58, v162
	v_fmac_f32_e32 v90, v59, v163
	v_fmac_f32_e32 v88, v56, v164
	v_fmac_f32_e32 v90, v57, v165
	ds_read_b128 v[162:165], v143 offset:4864
	s_waitcnt lgkmcnt(11)
	v_fmac_f32_e32 v88, v54, v166
	v_fmac_f32_e32 v90, v55, v167
	v_fmac_f32_e32 v88, v52, v168
	v_fmac_f32_e32 v90, v53, v169
	v_add_f32_e32 v84, v88, v90
	v_sub_f32_e32 v50, v50, v84
	ds_read_b128 v[166:169], v143 offset:4880
	s_waitcnt lgkmcnt(11)
	v_fma_f32 v88, v4, v114, 0
	v_fma_f32 v90, v5, v115, 0
	v_fmac_f32_e32 v88, v80, v116
	v_fmac_f32_e32 v90, v81, v117
	ds_read_b128 v[114:117], v143 offset:4896
	s_waitcnt lgkmcnt(11)
	v_fmac_f32_e32 v88, v82, v118
	v_fmac_f32_e32 v90, v83, v119
	v_fmac_f32_e32 v88, v60, v120
	v_fmac_f32_e32 v90, v61, v121
	ds_read_b128 v[118:121], v143 offset:4912
	s_waitcnt lgkmcnt(11)
	v_fmac_f32_e32 v88, v58, v122
	v_fmac_f32_e32 v90, v59, v123
	v_fmac_f32_e32 v88, v56, v124
	v_fmac_f32_e32 v90, v57, v125
	ds_read_b96 v[122:124], v143 offset:4928
	s_waitcnt lgkmcnt(11)
	v_fmac_f32_e32 v88, v54, v126
	v_fmac_f32_e32 v90, v55, v127
	v_fmac_f32_e32 v88, v52, v128
	v_fmac_f32_e32 v90, v53, v129
	ds_read_b128 v[126:129], v143 offset:5120
	s_waitcnt lgkmcnt(11)
	v_fmac_f32_e32 v88, v50, v130
	v_add_f32_e32 v84, v90, v88
	v_sub_f32_e32 v51, v51, v84
	ds_read_b128 v[130:133], v143 offset:5136
	s_waitcnt lgkmcnt(11)
	v_fma_f32 v88, v4, v134, 0
	v_fma_f32 v90, v5, v135, 0
	v_fmac_f32_e32 v88, v80, v136
	v_fmac_f32_e32 v90, v81, v137
	ds_read_b128 v[134:137], v143 offset:5152
	s_waitcnt lgkmcnt(11)
	v_fmac_f32_e32 v88, v82, v146
	v_fmac_f32_e32 v90, v83, v147
	v_fmac_f32_e32 v88, v60, v148
	v_fmac_f32_e32 v90, v61, v149
	ds_read_b128 v[146:149], v143 offset:5168
	s_waitcnt lgkmcnt(11)
	v_fmac_f32_e32 v88, v58, v150
	v_fmac_f32_e32 v90, v59, v151
	v_fmac_f32_e32 v88, v56, v152
	v_fmac_f32_e32 v90, v57, v153
	ds_read_b128 v[150:153], v143 offset:5184
	s_waitcnt lgkmcnt(11)
	v_fmac_f32_e32 v88, v54, v154
	v_fmac_f32_e32 v90, v55, v155
	v_fmac_f32_e32 v88, v52, v156
	v_fmac_f32_e32 v90, v53, v157
	ds_read_b128 v[154:157], v143 offset:5376
	s_waitcnt lgkmcnt(11)
	v_fmac_f32_e32 v88, v50, v158
	v_fmac_f32_e32 v90, v51, v159
	v_add_f32_e32 v84, v88, v90
	v_sub_f32_e32 v48, v48, v84
	ds_read_b128 v[158:161], v143 offset:5392
	s_waitcnt lgkmcnt(11)
	v_fma_f32 v88, v4, v162, 0
	v_fma_f32 v90, v5, v163, 0
	v_fmac_f32_e32 v88, v80, v164
	v_fmac_f32_e32 v90, v81, v165
	ds_read_b128 v[162:165], v143 offset:5408
	s_waitcnt lgkmcnt(11)
	v_fmac_f32_e32 v88, v82, v166
	v_fmac_f32_e32 v90, v83, v167
	v_fmac_f32_e32 v88, v60, v168
	v_fmac_f32_e32 v90, v61, v169
	ds_read_b128 v[166:169], v143 offset:5424
	s_waitcnt lgkmcnt(11)
	v_fmac_f32_e32 v88, v58, v114
	v_fmac_f32_e32 v90, v59, v115
	v_fmac_f32_e32 v88, v56, v116
	v_fmac_f32_e32 v90, v57, v117
	ds_read_b128 v[114:117], v143 offset:5440
	s_waitcnt lgkmcnt(11)
	v_fmac_f32_e32 v88, v54, v118
	v_fmac_f32_e32 v90, v55, v119
	v_fmac_f32_e32 v88, v52, v120
	v_fmac_f32_e32 v90, v53, v121
	ds_read_b32 v118, v143 offset:5456
	s_waitcnt lgkmcnt(11)
	v_fmac_f32_e32 v88, v50, v122
	v_fmac_f32_e32 v90, v51, v123
	v_fmac_f32_e32 v88, v48, v124
	v_add_f32_e32 v84, v90, v88
	v_sub_f32_e32 v49, v49, v84
	ds_read_b128 v[122:125], v143 offset:5632
	s_waitcnt lgkmcnt(11)
	v_fma_f32 v88, v4, v126, 0
	v_fma_f32 v90, v5, v127, 0
	v_fmac_f32_e32 v88, v80, v128
	v_fmac_f32_e32 v90, v81, v129
	ds_read_b128 v[126:129], v143 offset:5648
	s_waitcnt lgkmcnt(11)
	v_fmac_f32_e32 v88, v82, v130
	v_fmac_f32_e32 v90, v83, v131
	v_fmac_f32_e32 v88, v60, v132
	v_fmac_f32_e32 v90, v61, v133
	ds_read_b128 v[130:133], v143 offset:5664
	s_waitcnt lgkmcnt(11)
; DI void gdn_g1(const Params& p, int l, int ch, char* smem) {
;     ...
;     for (int cc = 1; cc < 64; ++cc) { float a0 = 0.f, a1 = 0.f;
; #pragma unroll
;       for (int s2 = 0; s2 < cc; ++s2) { if (s2 & 1) a1 += sA[cc * 64 + s2] * sol[s2]; else a0 += sA[cc * 64 + s2] * sol[s2]; }
;       sol[cc] -= a0 + a1; }
	v_fmac_f32_e32 v88, v58, v134
	v_fmac_f32_e32 v90, v59, v135
	v_fmac_f32_e32 v88, v56, v136
	v_fmac_f32_e32 v90, v57, v137
	ds_read_b128 v[134:137], v143 offset:5680
	s_waitcnt lgkmcnt(11)
	v_fmac_f32_e32 v88, v54, v146
	v_fmac_f32_e32 v90, v55, v147
	v_fmac_f32_e32 v88, v52, v148
	v_fmac_f32_e32 v90, v53, v149
	ds_read_b128 v[146:149], v143 offset:5696
	s_waitcnt lgkmcnt(11)
	v_fmac_f32_e32 v88, v50, v150
	v_fmac_f32_e32 v90, v51, v151
	v_fmac_f32_e32 v88, v48, v152
	v_fmac_f32_e32 v90, v49, v153
	v_add_f32_e32 v84, v88, v90
	v_sub_f32_e32 v46, v46, v84
	ds_read_b64 v[150:151], v143 offset:5712
	s_waitcnt lgkmcnt(11)
	v_fma_f32 v88, v4, v154, 0
	v_fma_f32 v90, v5, v155, 0
	v_fmac_f32_e32 v88, v80, v156
	v_fmac_f32_e32 v90, v81, v157
	ds_read_b128 v[154:157], v143 offset:5888
	s_waitcnt lgkmcnt(11)
	v_fmac_f32_e32 v88, v82, v158
	v_fmac_f32_e32 v90, v83, v159
	v_fmac_f32_e32 v88, v60, v160
	v_fmac_f32_e32 v90, v61, v161
	ds_read_b128 v[158:161], v143 offset:5904
	s_waitcnt lgkmcnt(11)
	v_fmac_f32_e32 v88, v58, v162
	v_fmac_f32_e32 v90, v59, v163
	v_fmac_f32_e32 v88, v56, v164
	v_fmac_f32_e32 v90, v57, v165
	ds_read_b128 v[162:165], v143 offset:5920
	s_waitcnt lgkmcnt(11)
	v_fmac_f32_e32 v88, v54, v166
	v_fmac_f32_e32 v90, v55, v167
	v_fmac_f32_e32 v88, v52, v168
	v_fmac_f32_e32 v90, v53, v169
	ds_read_b128 v[166:169], v143 offset:5936
	s_waitcnt lgkmcnt(11)
	v_fmac_f32_e32 v88, v50, v114
	v_fmac_f32_e32 v90, v51, v115
	v_fmac_f32_e32 v88, v48, v116
	v_fmac_f32_e32 v90, v49, v117
	ds_read_b128 v[114:117], v143 offset:5952
	s_waitcnt lgkmcnt(11)
	v_fmac_f32_e32 v88, v46, v118
	v_add_f32_e32 v84, v90, v88
	v_sub_f32_e32 v47, v47, v84
	ds_read_b96 v[118:120], v143 offset:5968
	s_waitcnt lgkmcnt(11)
	v_fma_f32 v88, v4, v122, 0
	v_fma_f32 v90, v5, v123, 0
	v_fmac_f32_e32 v88, v80, v124
	v_fmac_f32_e32 v90, v81, v125
	ds_read_b128 v[122:125], v143 offset:6144
	s_waitcnt lgkmcnt(11)
	v_fmac_f32_e32 v88, v82, v126
	v_fmac_f32_e32 v90, v83, v127
	v_fmac_f32_e32 v88, v60, v128
	v_fmac_f32_e32 v90, v61, v129
	ds_read_b128 v[126:129], v143 offset:6160
	s_waitcnt lgkmcnt(11)
	v_fmac_f32_e32 v88, v58, v130
	v_fmac_f32_e32 v90, v59, v131
	v_fmac_f32_e32 v88, v56, v132
	v_fmac_f32_e32 v90, v57, v133
	ds_read_b128 v[130:133], v143 offset:6176
	s_waitcnt lgkmcnt(11)
	v_fmac_f32_e32 v88, v54, v134
	v_fmac_f32_e32 v90, v55, v135
	v_fmac_f32_e32 v88, v52, v136
	v_fmac_f32_e32 v90, v53, v137
	ds_read_b128 v[134:137], v143 offset:6192
	s_waitcnt lgkmcnt(11)
	v_fmac_f32_e32 v88, v50, v146
	v_fmac_f32_e32 v90, v51, v147
	v_fmac_f32_e32 v88, v48, v148
	v_fmac_f32_e32 v90, v49, v149
	ds_read_b128 v[146:149], v143 offset:6208
	s_waitcnt lgkmcnt(11)
	v_fmac_f32_e32 v88, v46, v150
	v_fmac_f32_e32 v90, v47, v151
	v_add_f32_e32 v84, v88, v90
	v_sub_f32_e32 v44, v44, v84
	ds_read_b128 v[150:153], v143 offset:6224
	s_waitcnt lgkmcnt(11)
	v_fma_f32 v88, v4, v154, 0
	v_fma_f32 v90, v5, v155, 0
	v_fmac_f32_e32 v88, v80, v156
	v_fmac_f32_e32 v90, v81, v157
	ds_read_b128 v[154:157], v143 offset:6400
	s_waitcnt lgkmcnt(11)
	v_fmac_f32_e32 v88, v82, v158
	v_fmac_f32_e32 v90, v83, v159
	v_fmac_f32_e32 v88, v60, v160
	v_fmac_f32_e32 v90, v61, v161
	ds_read_b128 v[158:161], v143 offset:6416
	s_waitcnt lgkmcnt(11)
	v_fmac_f32_e32 v88, v58, v162
	v_fmac_f32_e32 v90, v59, v163
	v_fmac_f32_e32 v88, v56, v164
	v_fmac_f32_e32 v90, v57, v165
	ds_read_b128 v[162:165], v143 offset:6432
	s_waitcnt lgkmcnt(11)
	v_fmac_f32_e32 v88, v54, v166
	v_fmac_f32_e32 v90, v55, v167
	v_fmac_f32_e32 v88, v52, v168
	v_fmac_f32_e32 v90, v53, v169
	ds_read_b128 v[166:169], v143 offset:6448
	s_waitcnt lgkmcnt(11)
	v_fmac_f32_e32 v88, v50, v114
	v_fmac_f32_e32 v90, v51, v115
	v_fmac_f32_e32 v88, v48, v116
	v_fmac_f32_e32 v90, v49, v117
	ds_read_b128 v[114:117], v143 offset:6464
	s_waitcnt lgkmcnt(11)
	v_fmac_f32_e32 v88, v46, v118
	v_fmac_f32_e32 v90, v47, v119
	v_fmac_f32_e32 v88, v44, v120
	v_add_f32_e32 v84, v90, v88
	v_sub_f32_e32 v45, v45, v84
	ds_read_b128 v[118:121], v143 offset:6480
	s_waitcnt lgkmcnt(11)
	v_fma_f32 v88, v4, v122, 0
	v_fma_f32 v90, v5, v123, 0
	v_fmac_f32_e32 v88, v80, v124
	v_fmac_f32_e32 v90, v81, v125
	ds_read_b32 v122, v143 offset:6496
	s_waitcnt lgkmcnt(11)
	v_fmac_f32_e32 v88, v82, v126
	v_fmac_f32_e32 v90, v83, v127
	v_fmac_f32_e32 v88, v60, v128
	v_fmac_f32_e32 v90, v61, v129
	ds_read_b128 v[126:129], v143 offset:6656
	s_waitcnt lgkmcnt(11)
	v_fmac_f32_e32 v88, v58, v130
	v_fmac_f32_e32 v90, v59, v131
	v_fmac_f32_e32 v88, v56, v132
	v_fmac_f32_e32 v90, v57, v133
	ds_read_b128 v[130:133], v143 offset:6672
	s_waitcnt lgkmcnt(11)
	v_fmac_f32_e32 v88, v54, v134
	v_fmac_f32_e32 v90, v55, v135
	v_fmac_f32_e32 v88, v52, v136
	v_fmac_f32_e32 v90, v53, v137
	ds_read_b128 v[134:137], v143 offset:6688
	s_waitcnt lgkmcnt(11)
	v_fmac_f32_e32 v88, v50, v146
	v_fmac_f32_e32 v90, v51, v147
	v_fmac_f32_e32 v88, v48, v148
	v_fmac_f32_e32 v90, v49, v149
	ds_read_b128 v[146:149], v143 offset:6704
	s_waitcnt lgkmcnt(11)
	v_fmac_f32_e32 v88, v46, v150
	v_fmac_f32_e32 v90, v47, v151
	v_fmac_f32_e32 v88, v44, v152
	v_fmac_f32_e32 v90, v45, v153
	v_add_f32_e32 v84, v88, v90
	v_sub_f32_e32 v42, v42, v84
	ds_read_b128 v[150:153], v143 offset:6720
	s_waitcnt lgkmcnt(11)
	v_fma_f32 v88, v4, v154, 0
	v_fma_f32 v90, v5, v155, 0
	v_fmac_f32_e32 v88, v80, v156
	v_fmac_f32_e32 v90, v81, v157
	ds_read_b128 v[154:157], v143 offset:6736
	s_waitcnt lgkmcnt(11)
	v_fmac_f32_e32 v88, v82, v158
	v_fmac_f32_e32 v90, v83, v159
	v_fmac_f32_e32 v88, v60, v160
	v_fmac_f32_e32 v90, v61, v161
	ds_read_b64 v[158:159], v143 offset:6752
	s_waitcnt lgkmcnt(11)
; DI void gdn_g1(const Params& p, int l, int ch, char* smem) {
;     ...
;     for (int cc = 1; cc < 64; ++cc) { float a0 = 0.f, a1 = 0.f;
; #pragma unroll
;       for (int s2 = 0; s2 < cc; ++s2) { if (s2 & 1) a1 += sA[cc * 64 + s2] * sol[s2]; else a0 += sA[cc * 64 + s2] * sol[s2]; }
;       sol[cc] -= a0 + a1; }
	v_fmac_f32_e32 v88, v58, v162
	v_fmac_f32_e32 v90, v59, v163
	v_fmac_f32_e32 v88, v56, v164
	v_fmac_f32_e32 v90, v57, v165
	ds_read_b128 v[162:165], v143 offset:6912
	s_waitcnt lgkmcnt(11)
	v_fmac_f32_e32 v88, v54, v166
	v_fmac_f32_e32 v90, v55, v167
	v_fmac_f32_e32 v88, v52, v168
	v_fmac_f32_e32 v90, v53, v169
	ds_read_b128 v[166:169], v143 offset:6928
	s_waitcnt lgkmcnt(11)
	v_fmac_f32_e32 v88, v50, v114
	v_fmac_f32_e32 v90, v51, v115
	v_fmac_f32_e32 v88, v48, v116
	v_fmac_f32_e32 v90, v49, v117
	ds_read_b128 v[114:117], v143 offset:6944
	s_waitcnt lgkmcnt(11)
	v_fmac_f32_e32 v88, v46, v118
	v_fmac_f32_e32 v90, v47, v119
	v_fmac_f32_e32 v88, v44, v120
	v_fmac_f32_e32 v90, v45, v121
	ds_read_b128 v[118:121], v143 offset:6960
	s_waitcnt lgkmcnt(11)
	v_fmac_f32_e32 v88, v42, v122
	v_add_f32_e32 v84, v90, v88
	v_sub_f32_e32 v43, v43, v84
	ds_read_b128 v[122:125], v143 offset:6976
	s_waitcnt lgkmcnt(11)
	v_fma_f32 v88, v4, v126, 0
	v_fma_f32 v90, v5, v127, 0
	v_fmac_f32_e32 v88, v80, v128
	v_fmac_f32_e32 v90, v81, v129
	ds_read_b128 v[126:129], v143 offset:6992
	s_waitcnt lgkmcnt(11)
	v_fmac_f32_e32 v88, v82, v130
	v_fmac_f32_e32 v90, v83, v131
	v_fmac_f32_e32 v88, v60, v132
	v_fmac_f32_e32 v90, v61, v133
	ds_read_b96 v[130:132], v143 offset:7008
	s_waitcnt lgkmcnt(11)
	v_fmac_f32_e32 v88, v58, v134
	v_fmac_f32_e32 v90, v59, v135
	v_fmac_f32_e32 v88, v56, v136
	v_fmac_f32_e32 v90, v57, v137
	ds_read_b128 v[134:137], v143 offset:7168
	s_waitcnt lgkmcnt(11)
	v_fmac_f32_e32 v88, v54, v146
	v_fmac_f32_e32 v90, v55, v147
	v_fmac_f32_e32 v88, v52, v148
	v_fmac_f32_e32 v90, v53, v149
	ds_read_b128 v[146:149], v143 offset:7184
	s_waitcnt lgkmcnt(11)
	v_fmac_f32_e32 v88, v50, v150
	v_fmac_f32_e32 v90, v51, v151
	v_fmac_f32_e32 v88, v48, v152
	v_fmac_f32_e32 v90, v49, v153
	ds_read_b128 v[150:153], v143 offset:7200
	s_waitcnt lgkmcnt(11)
	v_fmac_f32_e32 v88, v46, v154
	v_fmac_f32_e32 v90, v47, v155
	v_fmac_f32_e32 v88, v44, v156
	v_fmac_f32_e32 v90, v45, v157
	ds_read_b128 v[154:157], v143 offset:7216
	s_waitcnt lgkmcnt(11)
	v_fmac_f32_e32 v88, v42, v158
	v_fmac_f32_e32 v90, v43, v159
	v_add_f32_e32 v84, v88, v90
	v_sub_f32_e32 v40, v40, v84
	ds_read_b128 v[158:161], v143 offset:7232
	s_waitcnt lgkmcnt(11)
	v_fma_f32 v88, v4, v162, 0
	v_fma_f32 v90, v5, v163, 0
	v_fmac_f32_e32 v88, v80, v164
	v_fmac_f32_e32 v90, v81, v165
	ds_read_b128 v[162:165], v143 offset:7248
	s_waitcnt lgkmcnt(11)
	v_fmac_f32_e32 v88, v82, v166
	v_fmac_f32_e32 v90, v83, v167
	v_fmac_f32_e32 v88, v60, v168
	v_fmac_f32_e32 v90, v61, v169
	ds_read_b128 v[166:169], v143 offset:7264
	s_waitcnt lgkmcnt(11)
	v_fmac_f32_e32 v88, v58, v114
	v_fmac_f32_e32 v90, v59, v115
	v_fmac_f32_e32 v88, v56, v116
	v_fmac_f32_e32 v90, v57, v117
	ds_read_b128 v[114:117], v143 offset:7424
	s_waitcnt lgkmcnt(11)
	v_fmac_f32_e32 v88, v54, v118
	v_fmac_f32_e32 v90, v55, v119
	v_fmac_f32_e32 v88, v52, v120
	v_fmac_f32_e32 v90, v53, v121
	ds_read_b128 v[118:121], v143 offset:7440
	s_waitcnt lgkmcnt(11)
	v_fmac_f32_e32 v88, v50, v122
	v_fmac_f32_e32 v90, v51, v123
	v_fmac_f32_e32 v88, v48, v124
	v_fmac_f32_e32 v90, v49, v125
	ds_read_b128 v[122:125], v143 offset:7456
	s_waitcnt lgkmcnt(11)
	v_fmac_f32_e32 v88, v46, v126
	v_fmac_f32_e32 v90, v47, v127
	v_fmac_f32_e32 v88, v44, v128
	v_fmac_f32_e32 v90, v45, v129
	ds_read_b128 v[126:129], v143 offset:7472
	s_waitcnt lgkmcnt(11)
	v_fmac_f32_e32 v88, v42, v130
	v_fmac_f32_e32 v90, v43, v131
	v_fmac_f32_e32 v88, v40, v132
	v_add_f32_e32 v84, v90, v88
	v_sub_f32_e32 v41, v41, v84
	ds_read_b128 v[130:133], v143 offset:7488
	s_waitcnt lgkmcnt(11)
	v_fma_f32 v88, v4, v134, 0
	v_fma_f32 v90, v5, v135, 0
	v_fmac_f32_e32 v88, v80, v136
	v_fmac_f32_e32 v90, v81, v137
	ds_read_b128 v[134:137], v143 offset:7504
	s_waitcnt lgkmcnt(11)
	v_fmac_f32_e32 v88, v82, v146
	v_fmac_f32_e32 v90, v83, v147
	v_fmac_f32_e32 v88, v60, v148
	v_fmac_f32_e32 v90, v61, v149
	ds_read_b128 v[146:149], v143 offset:7520
	s_waitcnt lgkmcnt(11)
	v_fmac_f32_e32 v88, v58, v150
	v_fmac_f32_e32 v90, v59, v151
	v_fmac_f32_e32 v88, v56, v152
	v_fmac_f32_e32 v90, v57, v153
	ds_read_b32 v150, v143 offset:7536
	s_waitcnt lgkmcnt(11)
	v_fmac_f32_e32 v88, v54, v154
	v_fmac_f32_e32 v90, v55, v155
	v_fmac_f32_e32 v88, v52, v156
	v_fmac_f32_e32 v90, v53, v157
	ds_read_b128 v[154:157], v143 offset:7680
	s_waitcnt lgkmcnt(11)
	v_fmac_f32_e32 v88, v50, v158
	v_fmac_f32_e32 v90, v51, v159
	v_fmac_f32_e32 v88, v48, v160
	v_fmac_f32_e32 v90, v49, v161
	ds_read_b128 v[158:161], v143 offset:7696
	s_waitcnt lgkmcnt(11)
	v_fmac_f32_e32 v88, v46, v162
	v_fmac_f32_e32 v90, v47, v163
	v_fmac_f32_e32 v88, v44, v164
	v_fmac_f32_e32 v90, v45, v165
	ds_read_b128 v[162:165], v143 offset:7712
	s_waitcnt lgkmcnt(11)
	v_fmac_f32_e32 v88, v42, v166
	v_fmac_f32_e32 v90, v43, v167
	v_fmac_f32_e32 v88, v40, v168
	v_fmac_f32_e32 v90, v41, v169
	v_add_f32_e32 v84, v88, v90
	v_sub_f32_e32 v38, v38, v84
	ds_read_b128 v[166:169], v143 offset:7728
	s_waitcnt lgkmcnt(11)
	v_fma_f32 v88, v4, v114, 0
	v_fma_f32 v90, v5, v115, 0
	v_fmac_f32_e32 v88, v80, v116
	v_fmac_f32_e32 v90, v81, v117
	ds_read_b128 v[114:117], v143 offset:7744
	s_waitcnt lgkmcnt(11)
	v_fmac_f32_e32 v88, v82, v118
	v_fmac_f32_e32 v90, v83, v119
	v_fmac_f32_e32 v88, v60, v120
	v_fmac_f32_e32 v90, v61, v121
	ds_read_b128 v[118:121], v143 offset:7760
	s_waitcnt lgkmcnt(11)
	v_fmac_f32_e32 v88, v58, v122
	v_fmac_f32_e32 v90, v59, v123
	v_fmac_f32_e32 v88, v56, v124
	v_fmac_f32_e32 v90, v57, v125
	ds_read_b128 v[122:125], v143 offset:7776
	s_waitcnt lgkmcnt(11)
	v_fmac_f32_e32 v88, v54, v126
	v_fmac_f32_e32 v90, v55, v127
	v_fmac_f32_e32 v88, v52, v128
	v_fmac_f32_e32 v90, v53, v129
	ds_read_b64 v[126:127], v143 offset:7792
	s_waitcnt lgkmcnt(11)
; DI void gdn_g1(const Params& p, int l, int ch, char* smem) {
;     ...
;     for (int cc = 1; cc < 64; ++cc) { float a0 = 0.f, a1 = 0.f;
; #pragma unroll
;       for (int s2 = 0; s2 < cc; ++s2) { if (s2 & 1) a1 += sA[cc * 64 + s2] * sol[s2]; else a0 += sA[cc * 64 + s2] * sol[s2]; }
;       sol[cc] -= a0 + a1; }
	v_fmac_f32_e32 v88, v50, v130
	v_fmac_f32_e32 v90, v51, v131
	v_fmac_f32_e32 v88, v48, v132
	v_fmac_f32_e32 v90, v49, v133
	ds_read_b128 v[130:133], v143 offset:7936
	s_waitcnt lgkmcnt(11)
	v_fmac_f32_e32 v88, v46, v134
	v_fmac_f32_e32 v90, v47, v135
	v_fmac_f32_e32 v88, v44, v136
	v_fmac_f32_e32 v90, v45, v137
	ds_read_b128 v[134:137], v143 offset:7952
	s_waitcnt lgkmcnt(11)
	v_fmac_f32_e32 v88, v42, v146
	v_fmac_f32_e32 v90, v43, v147
	v_fmac_f32_e32 v88, v40, v148
	v_fmac_f32_e32 v90, v41, v149
	ds_read_b128 v[146:149], v143 offset:7968
	s_waitcnt lgkmcnt(11)
	v_fmac_f32_e32 v88, v38, v150
	v_add_f32_e32 v84, v90, v88
	v_sub_f32_e32 v39, v39, v84
	ds_read_b128 v[150:153], v143 offset:7984
	s_waitcnt lgkmcnt(11)
	v_fma_f32 v88, v4, v154, 0
	v_fma_f32 v90, v5, v155, 0
	v_fmac_f32_e32 v88, v80, v156
	v_fmac_f32_e32 v90, v81, v157
	ds_read_b128 v[154:157], v143 offset:8000
	s_waitcnt lgkmcnt(11)
	v_fmac_f32_e32 v88, v82, v158
	v_fmac_f32_e32 v90, v83, v159
	v_fmac_f32_e32 v88, v60, v160
	v_fmac_f32_e32 v90, v61, v161
	ds_read_b128 v[158:161], v143 offset:8016
	s_waitcnt lgkmcnt(11)
	v_fmac_f32_e32 v88, v58, v162
	v_fmac_f32_e32 v90, v59, v163
	v_fmac_f32_e32 v88, v56, v164
	v_fmac_f32_e32 v90, v57, v165
	ds_read_b128 v[162:165], v143 offset:8032
	s_waitcnt lgkmcnt(11)
	v_fmac_f32_e32 v88, v54, v166
	v_fmac_f32_e32 v90, v55, v167
	v_fmac_f32_e32 v88, v52, v168
	v_fmac_f32_e32 v90, v53, v169
	ds_read_b96 v[166:168], v143 offset:8048
	s_waitcnt lgkmcnt(11)
	v_fmac_f32_e32 v88, v50, v114
	v_fmac_f32_e32 v90, v51, v115
	v_fmac_f32_e32 v88, v48, v116
	v_fmac_f32_e32 v90, v49, v117
	ds_read_b128 v[114:117], v143 offset:8192
	s_waitcnt lgkmcnt(11)
	v_fmac_f32_e32 v88, v46, v118
	v_fmac_f32_e32 v90, v47, v119
	v_fmac_f32_e32 v88, v44, v120
	v_fmac_f32_e32 v90, v45, v121
	ds_read_b128 v[118:121], v143 offset:8208
	s_waitcnt lgkmcnt(11)
	v_fmac_f32_e32 v88, v42, v122
	v_fmac_f32_e32 v90, v43, v123
	v_fmac_f32_e32 v88, v40, v124
	v_fmac_f32_e32 v90, v41, v125
	ds_read_b128 v[122:125], v143 offset:8224
	s_waitcnt lgkmcnt(11)
	v_fmac_f32_e32 v88, v38, v126
	v_fmac_f32_e32 v90, v39, v127
	v_add_f32_e32 v84, v88, v90
	v_sub_f32_e32 v36, v36, v84
	ds_read_b128 v[126:129], v143 offset:8240
	s_waitcnt lgkmcnt(11)
	v_fma_f32 v88, v4, v130, 0
	v_fma_f32 v90, v5, v131, 0
	v_fmac_f32_e32 v88, v80, v132
	v_fmac_f32_e32 v90, v81, v133
	ds_read_b128 v[130:133], v143 offset:8256
	s_waitcnt lgkmcnt(11)
	v_fmac_f32_e32 v88, v82, v134
	v_fmac_f32_e32 v90, v83, v135
	v_fmac_f32_e32 v88, v60, v136
	v_fmac_f32_e32 v90, v61, v137
	ds_read_b128 v[134:137], v143 offset:8272
	s_waitcnt lgkmcnt(11)
	v_fmac_f32_e32 v88, v58, v146
	v_fmac_f32_e32 v90, v59, v147
	v_fmac_f32_e32 v88, v56, v148
	v_fmac_f32_e32 v90, v57, v149
	ds_read_b128 v[146:149], v143 offset:8288
	s_waitcnt lgkmcnt(11)
	v_fmac_f32_e32 v88, v54, v150
	v_fmac_f32_e32 v90, v55, v151
	v_fmac_f32_e32 v88, v52, v152
	v_fmac_f32_e32 v90, v53, v153
	ds_read_b128 v[150:153], v143 offset:8304
	s_waitcnt lgkmcnt(11)
	v_fmac_f32_e32 v88, v50, v154
	v_fmac_f32_e32 v90, v51, v155
	v_fmac_f32_e32 v88, v48, v156
	v_fmac_f32_e32 v90, v49, v157
	ds_read_b128 v[154:157], v143 offset:8448
	s_waitcnt lgkmcnt(11)
	v_fmac_f32_e32 v88, v46, v158
	v_fmac_f32_e32 v90, v47, v159
	v_fmac_f32_e32 v88, v44, v160
	v_fmac_f32_e32 v90, v45, v161
	ds_read_b128 v[158:161], v143 offset:8464
	s_waitcnt lgkmcnt(11)
	v_fmac_f32_e32 v88, v42, v162
	v_fmac_f32_e32 v90, v43, v163
	v_fmac_f32_e32 v88, v40, v164
	v_fmac_f32_e32 v90, v41, v165
	ds_read_b128 v[162:165], v143 offset:8480
	s_waitcnt lgkmcnt(11)
	v_fmac_f32_e32 v88, v38, v166
	v_fmac_f32_e32 v90, v39, v167
	v_fmac_f32_e32 v88, v36, v168
	v_add_f32_e32 v84, v90, v88
	v_sub_f32_e32 v37, v37, v84
	ds_read_b128 v[166:169], v143 offset:8496
	s_waitcnt lgkmcnt(11)
	v_fma_f32 v88, v4, v114, 0
	v_fma_f32 v90, v5, v115, 0
	v_fmac_f32_e32 v88, v80, v116
	v_fmac_f32_e32 v90, v81, v117
	ds_read_b128 v[114:117], v143 offset:8512
	s_waitcnt lgkmcnt(11)
	v_fmac_f32_e32 v88, v82, v118
	v_fmac_f32_e32 v90, v83, v119
	v_fmac_f32_e32 v88, v60, v120
	v_fmac_f32_e32 v90, v61, v121
	ds_read_b128 v[118:121], v143 offset:8528
	s_waitcnt lgkmcnt(11)
	v_fmac_f32_e32 v88, v58, v122
	v_fmac_f32_e32 v90, v59, v123
	v_fmac_f32_e32 v88, v56, v124
	v_fmac_f32_e32 v90, v57, v125
	ds_read_b128 v[122:125], v143 offset:8544
	s_waitcnt lgkmcnt(11)
	v_fmac_f32_e32 v88, v54, v126
	v_fmac_f32_e32 v90, v55, v127
	v_fmac_f32_e32 v88, v52, v128
	v_fmac_f32_e32 v90, v53, v129
	ds_read_b128 v[126:129], v143 offset:8560
	s_waitcnt lgkmcnt(11)
	v_fmac_f32_e32 v88, v50, v130
	v_fmac_f32_e32 v90, v51, v131
	v_fmac_f32_e32 v88, v48, v132
	v_fmac_f32_e32 v90, v49, v133
	ds_read_b32 v130, v143 offset:8576
	s_waitcnt lgkmcnt(11)
	v_fmac_f32_e32 v88, v46, v134
	v_fmac_f32_e32 v90, v47, v135
	v_fmac_f32_e32 v88, v44, v136
	v_fmac_f32_e32 v90, v45, v137
	ds_read_b128 v[134:137], v143 offset:8704
	s_waitcnt lgkmcnt(11)
	v_fmac_f32_e32 v88, v42, v146
	v_fmac_f32_e32 v90, v43, v147
	v_fmac_f32_e32 v88, v40, v148
	v_fmac_f32_e32 v90, v41, v149
	ds_read_b128 v[146:149], v143 offset:8720
	s_waitcnt lgkmcnt(11)
	v_fmac_f32_e32 v88, v38, v150
	v_fmac_f32_e32 v90, v39, v151
	v_fmac_f32_e32 v88, v36, v152
	v_fmac_f32_e32 v90, v37, v153
	v_add_f32_e32 v84, v88, v90
	v_sub_f32_e32 v34, v34, v84
	ds_read_b128 v[150:153], v143 offset:8736
	s_waitcnt lgkmcnt(11)
	v_fma_f32 v88, v4, v154, 0
	v_fma_f32 v90, v5, v155, 0
	v_fmac_f32_e32 v88, v80, v156
	v_fmac_f32_e32 v90, v81, v157
	ds_read_b128 v[154:157], v143 offset:8752
	s_waitcnt lgkmcnt(11)
	v_fmac_f32_e32 v88, v82, v158
	v_fmac_f32_e32 v90, v83, v159
	v_fmac_f32_e32 v88, v60, v160
	v_fmac_f32_e32 v90, v61, v161
	ds_read_b128 v[158:161], v143 offset:8768
	s_waitcnt lgkmcnt(11)
; DI void gdn_g1(const Params& p, int l, int ch, char* smem) {
;     ...
;     for (int cc = 1; cc < 64; ++cc) { float a0 = 0.f, a1 = 0.f;
; #pragma unroll
;       for (int s2 = 0; s2 < cc; ++s2) { if (s2 & 1) a1 += sA[cc * 64 + s2] * sol[s2]; else a0 += sA[cc * 64 + s2] * sol[s2]; }
;       sol[cc] -= a0 + a1; }
	v_fmac_f32_e32 v88, v58, v162
	v_fmac_f32_e32 v90, v59, v163
	v_fmac_f32_e32 v88, v56, v164
	v_fmac_f32_e32 v90, v57, v165
	ds_read_b128 v[162:165], v143 offset:8784
	s_waitcnt lgkmcnt(11)
	v_fmac_f32_e32 v88, v54, v166
	v_fmac_f32_e32 v90, v55, v167
	v_fmac_f32_e32 v88, v52, v168
	v_fmac_f32_e32 v90, v53, v169
	ds_read_b128 v[166:169], v143 offset:8800
	s_waitcnt lgkmcnt(11)
	v_fmac_f32_e32 v88, v50, v114
	v_fmac_f32_e32 v90, v51, v115
	v_fmac_f32_e32 v88, v48, v116
	v_fmac_f32_e32 v90, v49, v117
	ds_read_b128 v[114:117], v143 offset:8816
	s_waitcnt lgkmcnt(11)
	v_fmac_f32_e32 v88, v46, v118
	v_fmac_f32_e32 v90, v47, v119
	v_fmac_f32_e32 v88, v44, v120
	v_fmac_f32_e32 v90, v45, v121
	ds_read_b64 v[118:119], v143 offset:8832
	s_waitcnt lgkmcnt(11)
	v_fmac_f32_e32 v88, v42, v122
	v_fmac_f32_e32 v90, v43, v123
	v_fmac_f32_e32 v88, v40, v124
	v_fmac_f32_e32 v90, v41, v125
	ds_read_b128 v[122:125], v143 offset:8960
	s_waitcnt lgkmcnt(11)
	v_fmac_f32_e32 v88, v38, v126
	v_fmac_f32_e32 v90, v39, v127
	v_fmac_f32_e32 v88, v36, v128
	v_fmac_f32_e32 v90, v37, v129
	ds_read_b128 v[126:129], v143 offset:8976
	s_waitcnt lgkmcnt(11)
	v_fmac_f32_e32 v88, v34, v130
	v_add_f32_e32 v84, v90, v88
	v_sub_f32_e32 v35, v35, v84
	ds_read_b128 v[130:133], v143 offset:8992
	s_waitcnt lgkmcnt(11)
	v_fma_f32 v88, v4, v134, 0
	v_fma_f32 v90, v5, v135, 0
	v_fmac_f32_e32 v88, v80, v136
	v_fmac_f32_e32 v90, v81, v137
	ds_read_b128 v[134:137], v143 offset:9008
	s_waitcnt lgkmcnt(11)
	v_fmac_f32_e32 v88, v82, v146
	v_fmac_f32_e32 v90, v83, v147
	v_fmac_f32_e32 v88, v60, v148
	v_fmac_f32_e32 v90, v61, v149
	ds_read_b128 v[146:149], v143 offset:9024
	s_waitcnt lgkmcnt(11)
	v_fmac_f32_e32 v88, v58, v150
	v_fmac_f32_e32 v90, v59, v151
	v_fmac_f32_e32 v88, v56, v152
	v_fmac_f32_e32 v90, v57, v153
	ds_read_b128 v[150:153], v143 offset:9040
	s_waitcnt lgkmcnt(11)
	v_fmac_f32_e32 v88, v54, v154
	v_fmac_f32_e32 v90, v55, v155
	v_fmac_f32_e32 v88, v52, v156
	v_fmac_f32_e32 v90, v53, v157
	ds_read_b128 v[154:157], v143 offset:9056
	s_waitcnt lgkmcnt(11)
	v_fmac_f32_e32 v88, v50, v158
	v_fmac_f32_e32 v90, v51, v159
	v_fmac_f32_e32 v88, v48, v160
	v_fmac_f32_e32 v90, v49, v161
	ds_read_b128 v[158:161], v143 offset:9072
	s_waitcnt lgkmcnt(11)
	v_fmac_f32_e32 v88, v46, v162
	v_fmac_f32_e32 v90, v47, v163
	v_fmac_f32_e32 v88, v44, v164
	v_fmac_f32_e32 v90, v45, v165
	ds_read_b96 v[162:164], v143 offset:9088
	s_waitcnt lgkmcnt(11)
	v_fmac_f32_e32 v88, v42, v166
	v_fmac_f32_e32 v90, v43, v167
	v_fmac_f32_e32 v88, v40, v168
	v_fmac_f32_e32 v90, v41, v169
	ds_read_b128 v[166:169], v143 offset:9216
	s_waitcnt lgkmcnt(11)
	v_fmac_f32_e32 v88, v38, v114
	v_fmac_f32_e32 v90, v39, v115
	v_fmac_f32_e32 v88, v36, v116
	v_fmac_f32_e32 v90, v37, v117
	ds_read_b128 v[114:117], v143 offset:9232
	s_waitcnt lgkmcnt(11)
	v_fmac_f32_e32 v88, v34, v118
	v_fmac_f32_e32 v90, v35, v119
	v_add_f32_e32 v84, v88, v90
	v_sub_f32_e32 v32, v32, v84
	ds_read_b128 v[118:121], v143 offset:9248
	s_waitcnt lgkmcnt(11)
	v_fma_f32 v88, v4, v122, 0
	v_fma_f32 v90, v5, v123, 0
	v_fmac_f32_e32 v88, v80, v124
	v_fmac_f32_e32 v90, v81, v125
	ds_read_b128 v[122:125], v143 offset:9264
	s_waitcnt lgkmcnt(11)
	v_fmac_f32_e32 v88, v82, v126
	v_fmac_f32_e32 v90, v83, v127
	v_fmac_f32_e32 v88, v60, v128
	v_fmac_f32_e32 v90, v61, v129
	ds_read_b128 v[126:129], v143 offset:9280
	s_waitcnt lgkmcnt(11)
	v_fmac_f32_e32 v88, v58, v130
	v_fmac_f32_e32 v90, v59, v131
	v_fmac_f32_e32 v88, v56, v132
	v_fmac_f32_e32 v90, v57, v133
	ds_read_b128 v[130:133], v143 offset:9296
	s_waitcnt lgkmcnt(11)
	v_fmac_f32_e32 v88, v54, v134
	v_fmac_f32_e32 v90, v55, v135
	v_fmac_f32_e32 v88, v52, v136
	v_fmac_f32_e32 v90, v53, v137
	ds_read_b128 v[134:137], v143 offset:9312
	s_waitcnt lgkmcnt(11)
	v_fmac_f32_e32 v88, v50, v146
	v_fmac_f32_e32 v90, v51, v147
	v_fmac_f32_e32 v88, v48, v148
	v_fmac_f32_e32 v90, v49, v149
	ds_read_b128 v[146:149], v143 offset:9328
	s_waitcnt lgkmcnt(11)
	v_fmac_f32_e32 v88, v46, v150
	v_fmac_f32_e32 v90, v47, v151
	v_fmac_f32_e32 v88, v44, v152
	v_fmac_f32_e32 v90, v45, v153
	ds_read_b128 v[150:153], v143 offset:9344
	s_waitcnt lgkmcnt(11)
	v_fmac_f32_e32 v88, v42, v154
	v_fmac_f32_e32 v90, v43, v155
	v_fmac_f32_e32 v88, v40, v156
	v_fmac_f32_e32 v90, v41, v157
	ds_read_b128 v[154:157], v143 offset:9472
	s_waitcnt lgkmcnt(11)
	v_fmac_f32_e32 v88, v38, v158
	v_fmac_f32_e32 v90, v39, v159
	v_fmac_f32_e32 v88, v36, v160
	v_fmac_f32_e32 v90, v37, v161
	ds_read_b128 v[158:161], v143 offset:9488
	s_waitcnt lgkmcnt(11)
	v_fmac_f32_e32 v88, v34, v162
	v_fmac_f32_e32 v90, v35, v163
	v_fmac_f32_e32 v88, v32, v164
	v_add_f32_e32 v84, v90, v88
	v_sub_f32_e32 v33, v33, v84
	ds_read_b128 v[162:165], v143 offset:9504
	s_waitcnt lgkmcnt(11)
	v_fma_f32 v88, v4, v166, 0
	v_fma_f32 v90, v5, v167, 0
	v_fmac_f32_e32 v88, v80, v168
	v_fmac_f32_e32 v90, v81, v169
	ds_read_b128 v[166:169], v143 offset:9520
	s_waitcnt lgkmcnt(11)
	v_fmac_f32_e32 v88, v82, v114
	v_fmac_f32_e32 v90, v83, v115
	v_fmac_f32_e32 v88, v60, v116
	v_fmac_f32_e32 v90, v61, v117
	ds_read_b128 v[114:117], v143 offset:9536
	s_waitcnt lgkmcnt(11)
	v_fmac_f32_e32 v88, v58, v118
	v_fmac_f32_e32 v90, v59, v119
	v_fmac_f32_e32 v88, v56, v120
	v_fmac_f32_e32 v90, v57, v121
	ds_read_b128 v[118:121], v143 offset:9552
	s_waitcnt lgkmcnt(11)
	v_fmac_f32_e32 v88, v54, v122
	v_fmac_f32_e32 v90, v55, v123
	v_fmac_f32_e32 v88, v52, v124
	v_fmac_f32_e32 v90, v53, v125
	ds_read_b128 v[122:125], v143 offset:9568
	s_waitcnt lgkmcnt(11)
	v_fmac_f32_e32 v88, v50, v126
	v_fmac_f32_e32 v90, v51, v127
	v_fmac_f32_e32 v88, v48, v128
	v_fmac_f32_e32 v90, v49, v129
	ds_read_b128 v[126:129], v143 offset:9584
	s_waitcnt lgkmcnt(11)
; DI void gdn_g1(const Params& p, int l, int ch, char* smem) {
;     ...
;     for (int cc = 1; cc < 64; ++cc) { float a0 = 0.f, a1 = 0.f;
; #pragma unroll
;       for (int s2 = 0; s2 < cc; ++s2) { if (s2 & 1) a1 += sA[cc * 64 + s2] * sol[s2]; else a0 += sA[cc * 64 + s2] * sol[s2]; }
;       sol[cc] -= a0 + a1; }
	v_fmac_f32_e32 v88, v46, v130
	v_fmac_f32_e32 v90, v47, v131
	v_fmac_f32_e32 v88, v44, v132
	v_fmac_f32_e32 v90, v45, v133
	ds_read_b128 v[130:133], v143 offset:9600
	s_waitcnt lgkmcnt(11)
	v_fmac_f32_e32 v88, v42, v134
	v_fmac_f32_e32 v90, v43, v135
	v_fmac_f32_e32 v88, v40, v136
	v_fmac_f32_e32 v90, v41, v137
	ds_read_b32 v134, v143 offset:9616
	s_waitcnt lgkmcnt(11)
	v_fmac_f32_e32 v88, v38, v146
	v_fmac_f32_e32 v90, v39, v147
	v_fmac_f32_e32 v88, v36, v148
	v_fmac_f32_e32 v90, v37, v149
	ds_read_b128 v[146:149], v143 offset:9728
	s_waitcnt lgkmcnt(11)
	v_fmac_f32_e32 v88, v34, v150
	v_fmac_f32_e32 v90, v35, v151
	v_fmac_f32_e32 v88, v32, v152
	v_fmac_f32_e32 v90, v33, v153
	v_add_f32_e32 v84, v88, v90
	v_sub_f32_e32 v30, v30, v84
	ds_read_b128 v[150:153], v143 offset:9744
	s_waitcnt lgkmcnt(11)
	v_fma_f32 v88, v4, v154, 0
	v_fma_f32 v90, v5, v155, 0
	v_fmac_f32_e32 v88, v80, v156
	v_fmac_f32_e32 v90, v81, v157
	ds_read_b128 v[154:157], v143 offset:9760
	s_waitcnt lgkmcnt(11)
	v_fmac_f32_e32 v88, v82, v158
	v_fmac_f32_e32 v90, v83, v159
	v_fmac_f32_e32 v88, v60, v160
	v_fmac_f32_e32 v90, v61, v161
	ds_read_b128 v[158:161], v143 offset:9776
	s_waitcnt lgkmcnt(11)
	v_fmac_f32_e32 v88, v58, v162
	v_fmac_f32_e32 v90, v59, v163
	v_fmac_f32_e32 v88, v56, v164
	v_fmac_f32_e32 v90, v57, v165
	ds_read_b128 v[162:165], v143 offset:9792
	s_waitcnt lgkmcnt(11)
	v_fmac_f32_e32 v88, v54, v166
	v_fmac_f32_e32 v90, v55, v167
	v_fmac_f32_e32 v88, v52, v168
	v_fmac_f32_e32 v90, v53, v169
	ds_read_b128 v[166:169], v143 offset:9808
	s_waitcnt lgkmcnt(11)
	v_fmac_f32_e32 v88, v50, v114
	v_fmac_f32_e32 v90, v51, v115
	v_fmac_f32_e32 v88, v48, v116
	v_fmac_f32_e32 v90, v49, v117
	ds_read_b128 v[114:117], v143 offset:9824
	s_waitcnt lgkmcnt(11)
	v_fmac_f32_e32 v88, v46, v118
	v_fmac_f32_e32 v90, v47, v119
	v_fmac_f32_e32 v88, v44, v120
	v_fmac_f32_e32 v90, v45, v121
	ds_read_b128 v[118:121], v143 offset:9840
	s_waitcnt lgkmcnt(11)
	v_fmac_f32_e32 v88, v42, v122
	v_fmac_f32_e32 v90, v43, v123
	v_fmac_f32_e32 v88, v40, v124
	v_fmac_f32_e32 v90, v41, v125
	ds_read_b128 v[122:125], v143 offset:9856
	s_waitcnt lgkmcnt(11)
	v_fmac_f32_e32 v88, v38, v126
	v_fmac_f32_e32 v90, v39, v127
	v_fmac_f32_e32 v88, v36, v128
	v_fmac_f32_e32 v90, v37, v129
	ds_read_b64 v[126:127], v143 offset:9872
	s_waitcnt lgkmcnt(11)
	v_fmac_f32_e32 v88, v34, v130
	v_fmac_f32_e32 v90, v35, v131
	v_fmac_f32_e32 v88, v32, v132
	v_fmac_f32_e32 v90, v33, v133
	ds_read_b128 v[130:133], v143 offset:9984
	s_waitcnt lgkmcnt(11)
	v_fmac_f32_e32 v88, v30, v134
	v_add_f32_e32 v84, v90, v88
	v_sub_f32_e32 v31, v31, v84
	ds_read_b128 v[134:137], v143 offset:10000
	s_waitcnt lgkmcnt(11)
	v_fma_f32 v88, v4, v146, 0
	v_fma_f32 v90, v5, v147, 0
	v_fmac_f32_e32 v88, v80, v148
	v_fmac_f32_e32 v90, v81, v149
	ds_read_b128 v[146:149], v143 offset:10016
	s_waitcnt lgkmcnt(11)
	v_fmac_f32_e32 v88, v82, v150
	v_fmac_f32_e32 v90, v83, v151
	v_fmac_f32_e32 v88, v60, v152
	v_fmac_f32_e32 v90, v61, v153
	ds_read_b128 v[150:153], v143 offset:10032
	s_waitcnt lgkmcnt(11)
	v_fmac_f32_e32 v88, v58, v154
	v_fmac_f32_e32 v90, v59, v155
	v_fmac_f32_e32 v88, v56, v156
	v_fmac_f32_e32 v90, v57, v157
	ds_read_b128 v[154:157], v143 offset:10048
	s_waitcnt lgkmcnt(11)
	v_fmac_f32_e32 v88, v54, v158
	v_fmac_f32_e32 v90, v55, v159
	v_fmac_f32_e32 v88, v52, v160
	v_fmac_f32_e32 v90, v53, v161
	ds_read_b128 v[158:161], v143 offset:10064
	s_waitcnt lgkmcnt(11)
	v_fmac_f32_e32 v88, v50, v162
	v_fmac_f32_e32 v90, v51, v163
	v_fmac_f32_e32 v88, v48, v164
	v_fmac_f32_e32 v90, v49, v165
	ds_read_b128 v[162:165], v143 offset:10080
	s_waitcnt lgkmcnt(11)
	v_fmac_f32_e32 v88, v46, v166
	v_fmac_f32_e32 v90, v47, v167
	v_fmac_f32_e32 v88, v44, v168
	v_fmac_f32_e32 v90, v45, v169
	ds_read_b128 v[166:169], v143 offset:10096
	s_waitcnt lgkmcnt(11)
	v_fmac_f32_e32 v88, v42, v114
	v_fmac_f32_e32 v90, v43, v115
	v_fmac_f32_e32 v88, v40, v116
	v_fmac_f32_e32 v90, v41, v117
	ds_read_b128 v[114:117], v143 offset:10112
	s_waitcnt lgkmcnt(11)
	v_fmac_f32_e32 v88, v38, v118
	v_fmac_f32_e32 v90, v39, v119
	v_fmac_f32_e32 v88, v36, v120
	v_fmac_f32_e32 v90, v37, v121
	ds_read_b96 v[118:120], v143 offset:10128
	s_waitcnt lgkmcnt(11)
	v_fmac_f32_e32 v88, v34, v122
	v_fmac_f32_e32 v90, v35, v123
	v_fmac_f32_e32 v88, v32, v124
	v_fmac_f32_e32 v90, v33, v125
	ds_read_b128 v[122:125], v143 offset:10240
	s_waitcnt lgkmcnt(11)
	v_fmac_f32_e32 v88, v30, v126
	v_fmac_f32_e32 v90, v31, v127
	v_add_f32_e32 v84, v88, v90
	v_sub_f32_e32 v28, v28, v84
	ds_read_b128 v[126:129], v143 offset:10256
	s_waitcnt lgkmcnt(11)
	v_fma_f32 v88, v4, v130, 0
	v_fma_f32 v90, v5, v131, 0
	v_fmac_f32_e32 v88, v80, v132
	v_fmac_f32_e32 v90, v81, v133
	ds_read_b128 v[130:133], v143 offset:10272
	s_waitcnt lgkmcnt(11)
	v_fmac_f32_e32 v88, v82, v134
	v_fmac_f32_e32 v90, v83, v135
	v_fmac_f32_e32 v88, v60, v136
	v_fmac_f32_e32 v90, v61, v137
	ds_read_b128 v[134:137], v143 offset:10288
	s_waitcnt lgkmcnt(11)
	v_fmac_f32_e32 v88, v58, v146
	v_fmac_f32_e32 v90, v59, v147
	v_fmac_f32_e32 v88, v56, v148
	v_fmac_f32_e32 v90, v57, v149
	ds_read_b128 v[146:149], v143 offset:10304
	s_waitcnt lgkmcnt(11)
	v_fmac_f32_e32 v88, v54, v150
	v_fmac_f32_e32 v90, v55, v151
	v_fmac_f32_e32 v88, v52, v152
	v_fmac_f32_e32 v90, v53, v153
	ds_read_b128 v[150:153], v143 offset:10320
	s_waitcnt lgkmcnt(11)
	v_fmac_f32_e32 v88, v50, v154
	v_fmac_f32_e32 v90, v51, v155
	v_fmac_f32_e32 v88, v48, v156
	v_fmac_f32_e32 v90, v49, v157
	ds_read_b128 v[154:157], v143 offset:10336
	s_waitcnt lgkmcnt(11)
	v_fmac_f32_e32 v88, v46, v158
	v_fmac_f32_e32 v90, v47, v159
	v_fmac_f32_e32 v88, v44, v160
	v_fmac_f32_e32 v90, v45, v161
	ds_read_b128 v[158:161], v143 offset:10352
	s_waitcnt lgkmcnt(11)
; DI void gdn_g1(const Params& p, int l, int ch, char* smem) {
;     ...
;     for (int cc = 1; cc < 64; ++cc) { float a0 = 0.f, a1 = 0.f;
; #pragma unroll
;       for (int s2 = 0; s2 < cc; ++s2) { if (s2 & 1) a1 += sA[cc * 64 + s2] * sol[s2]; else a0 += sA[cc * 64 + s2] * sol[s2]; }
;       sol[cc] -= a0 + a1; }
	v_fmac_f32_e32 v88, v42, v162
	v_fmac_f32_e32 v90, v43, v163
	v_fmac_f32_e32 v88, v40, v164
	v_fmac_f32_e32 v90, v41, v165
	ds_read_b128 v[162:165], v143 offset:10368
	s_waitcnt lgkmcnt(11)
	v_fmac_f32_e32 v88, v38, v166
	v_fmac_f32_e32 v90, v39, v167
	v_fmac_f32_e32 v88, v36, v168
	v_fmac_f32_e32 v90, v37, v169
	ds_read_b128 v[166:169], v143 offset:10384
	s_waitcnt lgkmcnt(11)
	v_fmac_f32_e32 v88, v34, v114
	v_fmac_f32_e32 v90, v35, v115
	v_fmac_f32_e32 v88, v32, v116
	v_fmac_f32_e32 v90, v33, v117
	ds_read_b128 v[114:117], v143 offset:10496
	s_waitcnt lgkmcnt(11)
	v_fmac_f32_e32 v88, v30, v118
	v_fmac_f32_e32 v90, v31, v119
	v_fmac_f32_e32 v88, v28, v120
	v_add_f32_e32 v84, v90, v88
	v_sub_f32_e32 v29, v29, v84
	ds_read_b128 v[118:121], v143 offset:10512
	s_waitcnt lgkmcnt(11)
	v_fma_f32 v88, v4, v122, 0
	v_fma_f32 v90, v5, v123, 0
	v_fmac_f32_e32 v88, v80, v124
	v_fmac_f32_e32 v90, v81, v125
	ds_read_b128 v[122:125], v143 offset:10528
	s_waitcnt lgkmcnt(11)
	v_fmac_f32_e32 v88, v82, v126
	v_fmac_f32_e32 v90, v83, v127
	v_fmac_f32_e32 v88, v60, v128
	v_fmac_f32_e32 v90, v61, v129
	ds_read_b128 v[126:129], v143 offset:10544
	s_waitcnt lgkmcnt(11)
	v_fmac_f32_e32 v88, v58, v130
	v_fmac_f32_e32 v90, v59, v131
	v_fmac_f32_e32 v88, v56, v132
	v_fmac_f32_e32 v90, v57, v133
	ds_read_b128 v[130:133], v143 offset:10560
	s_waitcnt lgkmcnt(11)
	v_fmac_f32_e32 v88, v54, v134
	v_fmac_f32_e32 v90, v55, v135
	v_fmac_f32_e32 v88, v52, v136
	v_fmac_f32_e32 v90, v53, v137
	ds_read_b128 v[134:137], v143 offset:10576
	s_waitcnt lgkmcnt(11)
	v_fmac_f32_e32 v88, v50, v146
	v_fmac_f32_e32 v90, v51, v147
	v_fmac_f32_e32 v88, v48, v148
	v_fmac_f32_e32 v90, v49, v149
	ds_read_b128 v[146:149], v143 offset:10592
	s_waitcnt lgkmcnt(11)
	v_fmac_f32_e32 v88, v46, v150
	v_fmac_f32_e32 v90, v47, v151
	v_fmac_f32_e32 v88, v44, v152
	v_fmac_f32_e32 v90, v45, v153
	ds_read_b128 v[150:153], v143 offset:10608
	s_waitcnt lgkmcnt(11)
	v_fmac_f32_e32 v88, v42, v154
	v_fmac_f32_e32 v90, v43, v155
	v_fmac_f32_e32 v88, v40, v156
	v_fmac_f32_e32 v90, v41, v157
	ds_read_b128 v[154:157], v143 offset:10624
	s_waitcnt lgkmcnt(11)
	v_fmac_f32_e32 v88, v38, v158
	v_fmac_f32_e32 v90, v39, v159
	v_fmac_f32_e32 v88, v36, v160
	v_fmac_f32_e32 v90, v37, v161
	ds_read_b128 v[158:161], v143 offset:10640
	s_waitcnt lgkmcnt(11)
	v_fmac_f32_e32 v88, v34, v162
	v_fmac_f32_e32 v90, v35, v163
	v_fmac_f32_e32 v88, v32, v164
	v_fmac_f32_e32 v90, v33, v165
	ds_read_b32 v162, v143 offset:10656
	s_waitcnt lgkmcnt(11)
	v_fmac_f32_e32 v88, v30, v166
	v_fmac_f32_e32 v90, v31, v167
	v_fmac_f32_e32 v88, v28, v168
	v_fmac_f32_e32 v90, v29, v169
	v_add_f32_e32 v84, v88, v90
	v_sub_f32_e32 v26, v26, v84
	ds_read_b128 v[166:169], v143 offset:10752
	s_waitcnt lgkmcnt(11)
	v_fma_f32 v88, v4, v114, 0
	v_fma_f32 v90, v5, v115, 0
	v_fmac_f32_e32 v88, v80, v116
	v_fmac_f32_e32 v90, v81, v117
	ds_read_b128 v[114:117], v143 offset:10768
	s_waitcnt lgkmcnt(11)
	v_fmac_f32_e32 v88, v82, v118
	v_fmac_f32_e32 v90, v83, v119
	v_fmac_f32_e32 v88, v60, v120
	v_fmac_f32_e32 v90, v61, v121
	ds_read_b128 v[118:121], v143 offset:10784
	s_waitcnt lgkmcnt(11)
	v_fmac_f32_e32 v88, v58, v122
	v_fmac_f32_e32 v90, v59, v123
	v_fmac_f32_e32 v88, v56, v124
	v_fmac_f32_e32 v90, v57, v125
	ds_read_b128 v[122:125], v143 offset:10800
	s_waitcnt lgkmcnt(11)
	v_fmac_f32_e32 v88, v54, v126
	v_fmac_f32_e32 v90, v55, v127
	v_fmac_f32_e32 v88, v52, v128
	v_fmac_f32_e32 v90, v53, v129
	ds_read_b128 v[126:129], v143 offset:10816
	s_waitcnt lgkmcnt(11)
	v_fmac_f32_e32 v88, v50, v130
	v_fmac_f32_e32 v90, v51, v131
	v_fmac_f32_e32 v88, v48, v132
	v_fmac_f32_e32 v90, v49, v133
	ds_read_b128 v[130:133], v143 offset:10832
	s_waitcnt lgkmcnt(11)
	v_fmac_f32_e32 v88, v46, v134
	v_fmac_f32_e32 v90, v47, v135
	v_fmac_f32_e32 v88, v44, v136
	v_fmac_f32_e32 v90, v45, v137
	ds_read_b128 v[134:137], v143 offset:10848
	s_waitcnt lgkmcnt(11)
	v_fmac_f32_e32 v88, v42, v146
	v_fmac_f32_e32 v90, v43, v147
	v_fmac_f32_e32 v88, v40, v148
	v_fmac_f32_e32 v90, v41, v149
	ds_read_b128 v[146:149], v143 offset:10864
	s_waitcnt lgkmcnt(11)
	v_fmac_f32_e32 v88, v38, v150
	v_fmac_f32_e32 v90, v39, v151
	v_fmac_f32_e32 v88, v36, v152
	v_fmac_f32_e32 v90, v37, v153
	ds_read_b128 v[150:153], v143 offset:10880
	s_waitcnt lgkmcnt(11)
	v_fmac_f32_e32 v88, v34, v154
	v_fmac_f32_e32 v90, v35, v155
	v_fmac_f32_e32 v88, v32, v156
	v_fmac_f32_e32 v90, v33, v157
	ds_read_b128 v[154:157], v143 offset:10896
	s_waitcnt lgkmcnt(11)
	v_fmac_f32_e32 v88, v30, v158
	v_fmac_f32_e32 v90, v31, v159
	v_fmac_f32_e32 v88, v28, v160
	v_fmac_f32_e32 v90, v29, v161
	ds_read_b64 v[158:159], v143 offset:10912
	s_waitcnt lgkmcnt(11)
	v_fmac_f32_e32 v88, v26, v162
	v_add_f32_e32 v84, v90, v88
	v_sub_f32_e32 v27, v27, v84
	ds_read_b128 v[162:165], v143 offset:11008
	s_waitcnt lgkmcnt(11)
	v_fma_f32 v88, v4, v166, 0
	v_fma_f32 v90, v5, v167, 0
	v_fmac_f32_e32 v88, v80, v168
	v_fmac_f32_e32 v90, v81, v169
	ds_read_b128 v[166:169], v143 offset:11024
	s_waitcnt lgkmcnt(11)
	v_fmac_f32_e32 v88, v82, v114
	v_fmac_f32_e32 v90, v83, v115
	v_fmac_f32_e32 v88, v60, v116
	v_fmac_f32_e32 v90, v61, v117
	ds_read_b128 v[114:117], v143 offset:11040
	s_waitcnt lgkmcnt(11)
	v_fmac_f32_e32 v88, v58, v118
	v_fmac_f32_e32 v90, v59, v119
	v_fmac_f32_e32 v88, v56, v120
	v_fmac_f32_e32 v90, v57, v121
	ds_read_b128 v[118:121], v143 offset:11056
	s_waitcnt lgkmcnt(11)
	v_fmac_f32_e32 v88, v54, v122
	v_fmac_f32_e32 v90, v55, v123
	v_fmac_f32_e32 v88, v52, v124
	v_fmac_f32_e32 v90, v53, v125
	ds_read_b128 v[122:125], v143 offset:11072
	s_waitcnt lgkmcnt(11)
; DI void gdn_g1(const Params& p, int l, int ch, char* smem) {
;     ...
;     for (int cc = 1; cc < 64; ++cc) { float a0 = 0.f, a1 = 0.f;
; #pragma unroll
;       for (int s2 = 0; s2 < cc; ++s2) { if (s2 & 1) a1 += sA[cc * 64 + s2] * sol[s2]; else a0 += sA[cc * 64 + s2] * sol[s2]; }
;       sol[cc] -= a0 + a1; }
	v_fmac_f32_e32 v88, v50, v126
	v_fmac_f32_e32 v90, v51, v127
	v_fmac_f32_e32 v88, v48, v128
	v_fmac_f32_e32 v90, v49, v129
	ds_read_b128 v[126:129], v143 offset:11088
	s_waitcnt lgkmcnt(11)
	v_fmac_f32_e32 v88, v46, v130
	v_fmac_f32_e32 v90, v47, v131
	v_fmac_f32_e32 v88, v44, v132
	v_fmac_f32_e32 v90, v45, v133
	ds_read_b128 v[130:133], v143 offset:11104
	s_waitcnt lgkmcnt(11)
	v_fmac_f32_e32 v88, v42, v134
	v_fmac_f32_e32 v90, v43, v135
	v_fmac_f32_e32 v88, v40, v136
	v_fmac_f32_e32 v90, v41, v137
	ds_read_b128 v[134:137], v143 offset:11120
	s_waitcnt lgkmcnt(11)
	v_fmac_f32_e32 v88, v38, v146
	v_fmac_f32_e32 v90, v39, v147
	v_fmac_f32_e32 v88, v36, v148
	v_fmac_f32_e32 v90, v37, v149
	ds_read_b128 v[146:149], v143 offset:11136
	s_waitcnt lgkmcnt(11)
	v_fmac_f32_e32 v88, v34, v150
	v_fmac_f32_e32 v90, v35, v151
	v_fmac_f32_e32 v88, v32, v152
	v_fmac_f32_e32 v90, v33, v153
	ds_read_b128 v[150:153], v143 offset:11152
	s_waitcnt lgkmcnt(11)
	v_fmac_f32_e32 v88, v30, v154
	v_fmac_f32_e32 v90, v31, v155
	v_fmac_f32_e32 v88, v28, v156
	v_fmac_f32_e32 v90, v29, v157
	ds_read_b96 v[154:156], v143 offset:11168
	s_waitcnt lgkmcnt(11)
	v_fmac_f32_e32 v88, v26, v158
	v_fmac_f32_e32 v90, v27, v159
	v_add_f32_e32 v84, v88, v90
	v_sub_f32_e32 v24, v24, v84
	ds_read_b128 v[158:161], v143 offset:11264
	s_waitcnt lgkmcnt(11)
	v_fma_f32 v88, v4, v162, 0
	v_fma_f32 v90, v5, v163, 0
	v_fmac_f32_e32 v88, v80, v164
	v_fmac_f32_e32 v90, v81, v165
	ds_read_b128 v[162:165], v143 offset:11280
	s_waitcnt lgkmcnt(11)
	v_fmac_f32_e32 v88, v82, v166
	v_fmac_f32_e32 v90, v83, v167
	v_fmac_f32_e32 v88, v60, v168
	v_fmac_f32_e32 v90, v61, v169
	ds_read_b128 v[166:169], v143 offset:11296
	s_waitcnt lgkmcnt(11)
	v_fmac_f32_e32 v88, v58, v114
	v_fmac_f32_e32 v90, v59, v115
	v_fmac_f32_e32 v88, v56, v116
	v_fmac_f32_e32 v90, v57, v117
	ds_read_b128 v[114:117], v143 offset:11312
	s_waitcnt lgkmcnt(11)
	v_fmac_f32_e32 v88, v54, v118
	v_fmac_f32_e32 v90, v55, v119
	v_fmac_f32_e32 v88, v52, v120
	v_fmac_f32_e32 v90, v53, v121
	ds_read_b128 v[118:121], v143 offset:11328
	s_waitcnt lgkmcnt(11)
	v_fmac_f32_e32 v88, v50, v122
	v_fmac_f32_e32 v90, v51, v123
	v_fmac_f32_e32 v88, v48, v124
	v_fmac_f32_e32 v90, v49, v125
	ds_read_b128 v[122:125], v143 offset:11344
	s_waitcnt lgkmcnt(11)
	v_fmac_f32_e32 v88, v46, v126
	v_fmac_f32_e32 v90, v47, v127
	v_fmac_f32_e32 v88, v44, v128
	v_fmac_f32_e32 v90, v45, v129
	ds_read_b128 v[126:129], v143 offset:11360
	s_waitcnt lgkmcnt(11)
	v_fmac_f32_e32 v88, v42, v130
	v_fmac_f32_e32 v90, v43, v131
	v_fmac_f32_e32 v88, v40, v132
	v_fmac_f32_e32 v90, v41, v133
	ds_read_b128 v[130:133], v143 offset:11376
	s_waitcnt lgkmcnt(11)
	v_fmac_f32_e32 v88, v38, v134
	v_fmac_f32_e32 v90, v39, v135
	v_fmac_f32_e32 v88, v36, v136
	v_fmac_f32_e32 v90, v37, v137
	ds_read_b128 v[134:137], v143 offset:11392
	s_waitcnt lgkmcnt(11)
	v_fmac_f32_e32 v88, v34, v146
	v_fmac_f32_e32 v90, v35, v147
	v_fmac_f32_e32 v88, v32, v148
	v_fmac_f32_e32 v90, v33, v149
	ds_read_b128 v[146:149], v143 offset:11408
	s_waitcnt lgkmcnt(11)
	v_fmac_f32_e32 v88, v30, v150
	v_fmac_f32_e32 v90, v31, v151
	v_fmac_f32_e32 v88, v28, v152
	v_fmac_f32_e32 v90, v29, v153
	ds_read_b128 v[150:153], v143 offset:11424
	s_waitcnt lgkmcnt(11)
	v_fmac_f32_e32 v88, v26, v154
	v_fmac_f32_e32 v90, v27, v155
	v_fmac_f32_e32 v88, v24, v156
	v_add_f32_e32 v84, v90, v88
	v_sub_f32_e32 v25, v25, v84
	ds_read_b128 v[154:157], v143 offset:11520
	s_waitcnt lgkmcnt(11)
	v_fma_f32 v88, v4, v158, 0
	v_fma_f32 v90, v5, v159, 0
	v_fmac_f32_e32 v88, v80, v160
	v_fmac_f32_e32 v90, v81, v161
	ds_read_b128 v[158:161], v143 offset:11536
	s_waitcnt lgkmcnt(11)
	v_fmac_f32_e32 v88, v82, v162
	v_fmac_f32_e32 v90, v83, v163
	v_fmac_f32_e32 v88, v60, v164
	v_fmac_f32_e32 v90, v61, v165
	ds_read_b128 v[162:165], v143 offset:11552
	s_waitcnt lgkmcnt(11)
	v_fmac_f32_e32 v88, v58, v166
	v_fmac_f32_e32 v90, v59, v167
	v_fmac_f32_e32 v88, v56, v168
	v_fmac_f32_e32 v90, v57, v169
	ds_read_b128 v[166:169], v143 offset:11568
	s_waitcnt lgkmcnt(11)
	v_fmac_f32_e32 v88, v54, v114
	v_fmac_f32_e32 v90, v55, v115
	v_fmac_f32_e32 v88, v52, v116
	v_fmac_f32_e32 v90, v53, v117
	ds_read_b128 v[114:117], v143 offset:11584
	s_waitcnt lgkmcnt(11)
	v_fmac_f32_e32 v88, v50, v118
	v_fmac_f32_e32 v90, v51, v119
	v_fmac_f32_e32 v88, v48, v120
	v_fmac_f32_e32 v90, v49, v121
	ds_read_b128 v[118:121], v143 offset:11600
	s_waitcnt lgkmcnt(11)
	v_fmac_f32_e32 v88, v46, v122
	v_fmac_f32_e32 v90, v47, v123
	v_fmac_f32_e32 v88, v44, v124
	v_fmac_f32_e32 v90, v45, v125
	ds_read_b128 v[122:125], v143 offset:11616
	s_waitcnt lgkmcnt(11)
	v_fmac_f32_e32 v88, v42, v126
	v_fmac_f32_e32 v90, v43, v127
	v_fmac_f32_e32 v88, v40, v128
	v_fmac_f32_e32 v90, v41, v129
	ds_read_b128 v[126:129], v143 offset:11632
	s_waitcnt lgkmcnt(11)
	v_fmac_f32_e32 v88, v38, v130
	v_fmac_f32_e32 v90, v39, v131
	v_fmac_f32_e32 v88, v36, v132
	v_fmac_f32_e32 v90, v37, v133
	ds_read_b128 v[130:133], v143 offset:11648
	s_waitcnt lgkmcnt(11)
	v_fmac_f32_e32 v88, v34, v134
	v_fmac_f32_e32 v90, v35, v135
	v_fmac_f32_e32 v88, v32, v136
	v_fmac_f32_e32 v90, v33, v137
	ds_read_b128 v[134:137], v143 offset:11664
	s_waitcnt lgkmcnt(11)
	v_fmac_f32_e32 v88, v30, v146
	v_fmac_f32_e32 v90, v31, v147
	v_fmac_f32_e32 v88, v28, v148
	v_fmac_f32_e32 v90, v29, v149
	ds_read_b128 v[146:149], v143 offset:11680
	s_waitcnt lgkmcnt(11)
	v_fmac_f32_e32 v88, v26, v150
	v_fmac_f32_e32 v90, v27, v151
	v_fmac_f32_e32 v88, v24, v152
	v_fmac_f32_e32 v90, v25, v153
	v_add_f32_e32 v84, v88, v90
	v_sub_f32_e32 v22, v22, v84
	ds_read_b32 v150, v143 offset:11696
	s_waitcnt lgkmcnt(11)
; DI void gdn_g1(const Params& p, int l, int ch, char* smem) {
;     ...
;     for (int cc = 1; cc < 64; ++cc) { float a0 = 0.f, a1 = 0.f;
; #pragma unroll
;       for (int s2 = 0; s2 < cc; ++s2) { if (s2 & 1) a1 += sA[cc * 64 + s2] * sol[s2]; else a0 += sA[cc * 64 + s2] * sol[s2]; }
;       sol[cc] -= a0 + a1; }
	v_fma_f32 v88, v4, v154, 0
	v_fma_f32 v90, v5, v155, 0
	v_fmac_f32_e32 v88, v80, v156
	v_fmac_f32_e32 v90, v81, v157
	ds_read_b128 v[154:157], v143 offset:11776
	s_waitcnt lgkmcnt(11)
	v_fmac_f32_e32 v88, v82, v158
	v_fmac_f32_e32 v90, v83, v159
	v_fmac_f32_e32 v88, v60, v160
	v_fmac_f32_e32 v90, v61, v161
	ds_read_b128 v[158:161], v143 offset:11792
	s_waitcnt lgkmcnt(11)
	v_fmac_f32_e32 v88, v58, v162
	v_fmac_f32_e32 v90, v59, v163
	v_fmac_f32_e32 v88, v56, v164
	v_fmac_f32_e32 v90, v57, v165
	ds_read_b128 v[162:165], v143 offset:11808
	s_waitcnt lgkmcnt(11)
	v_fmac_f32_e32 v88, v54, v166
	v_fmac_f32_e32 v90, v55, v167
	v_fmac_f32_e32 v88, v52, v168
	v_fmac_f32_e32 v90, v53, v169
	ds_read_b128 v[166:169], v143 offset:11824
	s_waitcnt lgkmcnt(11)
	v_fmac_f32_e32 v88, v50, v114
	v_fmac_f32_e32 v90, v51, v115
	v_fmac_f32_e32 v88, v48, v116
	v_fmac_f32_e32 v90, v49, v117
	ds_read_b128 v[114:117], v143 offset:11840
	s_waitcnt lgkmcnt(11)
	v_fmac_f32_e32 v88, v46, v118
	v_fmac_f32_e32 v90, v47, v119
	v_fmac_f32_e32 v88, v44, v120
	v_fmac_f32_e32 v90, v45, v121
	ds_read_b128 v[118:121], v143 offset:11856
	s_waitcnt lgkmcnt(11)
	v_fmac_f32_e32 v88, v42, v122
	v_fmac_f32_e32 v90, v43, v123
	v_fmac_f32_e32 v88, v40, v124
	v_fmac_f32_e32 v90, v41, v125
	ds_read_b128 v[122:125], v143 offset:11872
	s_waitcnt lgkmcnt(11)
	v_fmac_f32_e32 v88, v38, v126
	v_fmac_f32_e32 v90, v39, v127
	v_fmac_f32_e32 v88, v36, v128
	v_fmac_f32_e32 v90, v37, v129
	ds_read_b128 v[126:129], v143 offset:11888
	s_waitcnt lgkmcnt(11)
	v_fmac_f32_e32 v88, v34, v130
	v_fmac_f32_e32 v90, v35, v131
	v_fmac_f32_e32 v88, v32, v132
	v_fmac_f32_e32 v90, v33, v133
	ds_read_b128 v[130:133], v143 offset:11904
	s_waitcnt lgkmcnt(11)
	v_fmac_f32_e32 v88, v30, v134
	v_fmac_f32_e32 v90, v31, v135
	v_fmac_f32_e32 v88, v28, v136
	v_fmac_f32_e32 v90, v29, v137
	ds_read_b128 v[134:137], v143 offset:11920
	s_waitcnt lgkmcnt(11)
	v_fmac_f32_e32 v88, v26, v146
	v_fmac_f32_e32 v90, v27, v147
	v_fmac_f32_e32 v88, v24, v148
	v_fmac_f32_e32 v90, v25, v149
	ds_read_b128 v[146:149], v143 offset:11936
	s_waitcnt lgkmcnt(11)
	v_fmac_f32_e32 v88, v22, v150
	v_add_f32_e32 v84, v90, v88
	v_sub_f32_e32 v23, v23, v84
	ds_read_b64 v[150:151], v143 offset:11952
	s_waitcnt lgkmcnt(11)
	v_fma_f32 v88, v4, v154, 0
	v_fma_f32 v90, v5, v155, 0
	v_fmac_f32_e32 v88, v80, v156
	v_fmac_f32_e32 v90, v81, v157
	ds_read_b128 v[154:157], v143 offset:12032
	s_waitcnt lgkmcnt(11)
	v_fmac_f32_e32 v88, v82, v158
	v_fmac_f32_e32 v90, v83, v159
	v_fmac_f32_e32 v88, v60, v160
	v_fmac_f32_e32 v90, v61, v161
	ds_read_b128 v[158:161], v143 offset:12048
	s_waitcnt lgkmcnt(11)
	v_fmac_f32_e32 v88, v58, v162
	v_fmac_f32_e32 v90, v59, v163
	v_fmac_f32_e32 v88, v56, v164
	v_fmac_f32_e32 v90, v57, v165
	ds_read_b128 v[162:165], v143 offset:12064
	s_waitcnt lgkmcnt(11)
	v_fmac_f32_e32 v88, v54, v166
	v_fmac_f32_e32 v90, v55, v167
	v_fmac_f32_e32 v88, v52, v168
	v_fmac_f32_e32 v90, v53, v169
	ds_read_b128 v[166:169], v143 offset:12080
	s_waitcnt lgkmcnt(11)
	v_fmac_f32_e32 v88, v50, v114
	v_fmac_f32_e32 v90, v51, v115
	v_fmac_f32_e32 v88, v48, v116
	v_fmac_f32_e32 v90, v49, v117
	ds_read_b128 v[114:117], v143 offset:12096
	s_waitcnt lgkmcnt(11)
	v_fmac_f32_e32 v88, v46, v118
	v_fmac_f32_e32 v90, v47, v119
	v_fmac_f32_e32 v88, v44, v120
	v_fmac_f32_e32 v90, v45, v121
	ds_read_b128 v[118:121], v143 offset:12112
	s_waitcnt lgkmcnt(11)
	v_fmac_f32_e32 v88, v42, v122
	v_fmac_f32_e32 v90, v43, v123
	v_fmac_f32_e32 v88, v40, v124
	v_fmac_f32_e32 v90, v41, v125
	ds_read_b128 v[122:125], v143 offset:12128
	s_waitcnt lgkmcnt(11)
	v_fmac_f32_e32 v88, v38, v126
	v_fmac_f32_e32 v90, v39, v127
	v_fmac_f32_e32 v88, v36, v128
	v_fmac_f32_e32 v90, v37, v129
	ds_read_b128 v[126:129], v143 offset:12144
	s_waitcnt lgkmcnt(11)
	v_fmac_f32_e32 v88, v34, v130
	v_fmac_f32_e32 v90, v35, v131
	v_fmac_f32_e32 v88, v32, v132
	v_fmac_f32_e32 v90, v33, v133
	ds_read_b128 v[130:133], v143 offset:12160
	s_waitcnt lgkmcnt(11)
	v_fmac_f32_e32 v88, v30, v134
	v_fmac_f32_e32 v90, v31, v135
	v_fmac_f32_e32 v88, v28, v136
	v_fmac_f32_e32 v90, v29, v137
	ds_read_b128 v[134:137], v143 offset:12176
	s_waitcnt lgkmcnt(11)
	v_fmac_f32_e32 v88, v26, v146
	v_fmac_f32_e32 v90, v27, v147
	v_fmac_f32_e32 v88, v24, v148
	v_fmac_f32_e32 v90, v25, v149
	ds_read_b128 v[146:149], v143 offset:12192
	s_waitcnt lgkmcnt(11)
	v_fmac_f32_e32 v88, v22, v150
	v_fmac_f32_e32 v90, v23, v151
	v_add_f32_e32 v84, v88, v90
	v_sub_f32_e32 v20, v20, v84
	ds_read_b96 v[150:152], v143 offset:12208
	s_waitcnt lgkmcnt(11)
	v_fma_f32 v88, v4, v154, 0
	v_fma_f32 v90, v5, v155, 0
	v_fmac_f32_e32 v88, v80, v156
	v_fmac_f32_e32 v90, v81, v157
	ds_read_b128 v[154:157], v143 offset:12288
	s_waitcnt lgkmcnt(11)
	v_fmac_f32_e32 v88, v82, v158
	v_fmac_f32_e32 v90, v83, v159
	v_fmac_f32_e32 v88, v60, v160
	v_fmac_f32_e32 v90, v61, v161
	ds_read_b128 v[158:161], v143 offset:12304
	s_waitcnt lgkmcnt(11)
	v_fmac_f32_e32 v88, v58, v162
	v_fmac_f32_e32 v90, v59, v163
	v_fmac_f32_e32 v88, v56, v164
	v_fmac_f32_e32 v90, v57, v165
	ds_read_b128 v[162:165], v143 offset:12320
	s_waitcnt lgkmcnt(11)
	v_fmac_f32_e32 v88, v54, v166
	v_fmac_f32_e32 v90, v55, v167
	v_fmac_f32_e32 v88, v52, v168
	v_fmac_f32_e32 v90, v53, v169
	ds_read_b128 v[166:169], v143 offset:12336
	s_waitcnt lgkmcnt(11)
	v_fmac_f32_e32 v88, v50, v114
	v_fmac_f32_e32 v90, v51, v115
	v_fmac_f32_e32 v88, v48, v116
	v_fmac_f32_e32 v90, v49, v117
	ds_read_b128 v[114:117], v143 offset:12352
	s_waitcnt lgkmcnt(11)
	v_fmac_f32_e32 v88, v46, v118
	v_fmac_f32_e32 v90, v47, v119
	v_fmac_f32_e32 v88, v44, v120
	v_fmac_f32_e32 v90, v45, v121
	ds_read_b128 v[118:121], v143 offset:12368
	s_waitcnt lgkmcnt(11)
; DI void gdn_g1(const Params& p, int l, int ch, char* smem) {
;     ...
;     for (int cc = 1; cc < 64; ++cc) { float a0 = 0.f, a1 = 0.f;
; #pragma unroll
;       for (int s2 = 0; s2 < cc; ++s2) { if (s2 & 1) a1 += sA[cc * 64 + s2] * sol[s2]; else a0 += sA[cc * 64 + s2] * sol[s2]; }
;       sol[cc] -= a0 + a1; }
	v_fmac_f32_e32 v88, v42, v122
	v_fmac_f32_e32 v90, v43, v123
	v_fmac_f32_e32 v88, v40, v124
	v_fmac_f32_e32 v90, v41, v125
	ds_read_b128 v[122:125], v143 offset:12384
	s_waitcnt lgkmcnt(11)
	v_fmac_f32_e32 v88, v38, v126
	v_fmac_f32_e32 v90, v39, v127
	v_fmac_f32_e32 v88, v36, v128
	v_fmac_f32_e32 v90, v37, v129
	ds_read_b128 v[126:129], v143 offset:12400
	s_waitcnt lgkmcnt(11)
	v_fmac_f32_e32 v88, v34, v130
	v_fmac_f32_e32 v90, v35, v131
	v_fmac_f32_e32 v88, v32, v132
	v_fmac_f32_e32 v90, v33, v133
	ds_read_b128 v[130:133], v143 offset:12416
	s_waitcnt lgkmcnt(11)
	v_fmac_f32_e32 v88, v30, v134
	v_fmac_f32_e32 v90, v31, v135
	v_fmac_f32_e32 v88, v28, v136
	v_fmac_f32_e32 v90, v29, v137
	ds_read_b128 v[134:137], v143 offset:12432
	s_waitcnt lgkmcnt(11)
	v_fmac_f32_e32 v88, v26, v146
	v_fmac_f32_e32 v90, v27, v147
	v_fmac_f32_e32 v88, v24, v148
	v_fmac_f32_e32 v90, v25, v149
	ds_read_b128 v[146:149], v143 offset:12448
	s_waitcnt lgkmcnt(11)
	v_fmac_f32_e32 v88, v22, v150
	v_fmac_f32_e32 v90, v23, v151
	v_fmac_f32_e32 v88, v20, v152
	v_add_f32_e32 v84, v90, v88
	v_sub_f32_e32 v21, v21, v84
	ds_read_b128 v[150:153], v143 offset:12464
	s_waitcnt lgkmcnt(11)
	v_fma_f32 v88, v4, v154, 0
	v_fma_f32 v90, v5, v155, 0
	v_fmac_f32_e32 v88, v80, v156
	v_fmac_f32_e32 v90, v81, v157
	ds_read_b128 v[154:157], v143 offset:12544
	s_waitcnt lgkmcnt(11)
	v_fmac_f32_e32 v88, v82, v158
	v_fmac_f32_e32 v90, v83, v159
	v_fmac_f32_e32 v88, v60, v160
	v_fmac_f32_e32 v90, v61, v161
	ds_read_b128 v[158:161], v143 offset:12560
	s_waitcnt lgkmcnt(11)
	v_fmac_f32_e32 v88, v58, v162
	v_fmac_f32_e32 v90, v59, v163
	v_fmac_f32_e32 v88, v56, v164
	v_fmac_f32_e32 v90, v57, v165
	ds_read_b128 v[162:165], v143 offset:12576
	s_waitcnt lgkmcnt(11)
	v_fmac_f32_e32 v88, v54, v166
	v_fmac_f32_e32 v90, v55, v167
	v_fmac_f32_e32 v88, v52, v168
	v_fmac_f32_e32 v90, v53, v169
	ds_read_b128 v[166:169], v143 offset:12592
	s_waitcnt lgkmcnt(11)
	v_fmac_f32_e32 v88, v50, v114
	v_fmac_f32_e32 v90, v51, v115
	v_fmac_f32_e32 v88, v48, v116
	v_fmac_f32_e32 v90, v49, v117
	ds_read_b128 v[114:117], v143 offset:12608
	s_waitcnt lgkmcnt(11)
	v_fmac_f32_e32 v88, v46, v118
	v_fmac_f32_e32 v90, v47, v119
	v_fmac_f32_e32 v88, v44, v120
	v_fmac_f32_e32 v90, v45, v121
	ds_read_b128 v[118:121], v143 offset:12624
	s_waitcnt lgkmcnt(11)
	v_fmac_f32_e32 v88, v42, v122
	v_fmac_f32_e32 v90, v43, v123
	v_fmac_f32_e32 v88, v40, v124
	v_fmac_f32_e32 v90, v41, v125
	ds_read_b128 v[122:125], v143 offset:12640
	s_waitcnt lgkmcnt(11)
	v_fmac_f32_e32 v88, v38, v126
	v_fmac_f32_e32 v90, v39, v127
	v_fmac_f32_e32 v88, v36, v128
	v_fmac_f32_e32 v90, v37, v129
	ds_read_b128 v[126:129], v143 offset:12656
	s_waitcnt lgkmcnt(11)
	v_fmac_f32_e32 v88, v34, v130
	v_fmac_f32_e32 v90, v35, v131
	v_fmac_f32_e32 v88, v32, v132
	v_fmac_f32_e32 v90, v33, v133
	ds_read_b128 v[130:133], v143 offset:12672
	s_waitcnt lgkmcnt(11)
	v_fmac_f32_e32 v88, v30, v134
	v_fmac_f32_e32 v90, v31, v135
	v_fmac_f32_e32 v88, v28, v136
	v_fmac_f32_e32 v90, v29, v137
	ds_read_b128 v[134:137], v143 offset:12688
	s_waitcnt lgkmcnt(11)
	v_fmac_f32_e32 v88, v26, v146
	v_fmac_f32_e32 v90, v27, v147
	v_fmac_f32_e32 v88, v24, v148
	v_fmac_f32_e32 v90, v25, v149
	ds_read_b128 v[146:149], v143 offset:12704
	s_waitcnt lgkmcnt(11)
	v_fmac_f32_e32 v88, v22, v150
	v_fmac_f32_e32 v90, v23, v151
	v_fmac_f32_e32 v88, v20, v152
	v_fmac_f32_e32 v90, v21, v153
	v_add_f32_e32 v84, v88, v90
	v_sub_f32_e32 v18, v18, v84
	ds_read_b128 v[150:153], v143 offset:12720
	s_waitcnt lgkmcnt(11)
	v_fma_f32 v88, v4, v154, 0
	v_fma_f32 v90, v5, v155, 0
	v_fmac_f32_e32 v88, v80, v156
	v_fmac_f32_e32 v90, v81, v157
	ds_read_b32 v154, v143 offset:12736
	s_waitcnt lgkmcnt(11)
	v_fmac_f32_e32 v88, v82, v158
	v_fmac_f32_e32 v90, v83, v159
	v_fmac_f32_e32 v88, v60, v160
	v_fmac_f32_e32 v90, v61, v161
	ds_read_b128 v[158:161], v143 offset:12800
	s_waitcnt lgkmcnt(11)
	v_fmac_f32_e32 v88, v58, v162
	v_fmac_f32_e32 v90, v59, v163
	v_fmac_f32_e32 v88, v56, v164
	v_fmac_f32_e32 v90, v57, v165
	ds_read_b128 v[162:165], v143 offset:12816
	s_waitcnt lgkmcnt(11)
	v_fmac_f32_e32 v88, v54, v166
	v_fmac_f32_e32 v90, v55, v167
	v_fmac_f32_e32 v88, v52, v168
	v_fmac_f32_e32 v90, v53, v169
	ds_read_b128 v[166:169], v143 offset:12832
	s_waitcnt lgkmcnt(11)
	v_fmac_f32_e32 v88, v50, v114
	v_fmac_f32_e32 v90, v51, v115
	v_fmac_f32_e32 v88, v48, v116
	v_fmac_f32_e32 v90, v49, v117
	ds_read_b128 v[114:117], v143 offset:12848
	s_waitcnt lgkmcnt(11)
	v_fmac_f32_e32 v88, v46, v118
	v_fmac_f32_e32 v90, v47, v119
	v_fmac_f32_e32 v88, v44, v120
	v_fmac_f32_e32 v90, v45, v121
	ds_read_b128 v[118:121], v143 offset:12864
	s_waitcnt lgkmcnt(11)
	v_fmac_f32_e32 v88, v42, v122
	v_fmac_f32_e32 v90, v43, v123
	v_fmac_f32_e32 v88, v40, v124
	v_fmac_f32_e32 v90, v41, v125
	ds_read_b128 v[122:125], v143 offset:12880
	s_waitcnt lgkmcnt(11)
	v_fmac_f32_e32 v88, v38, v126
	v_fmac_f32_e32 v90, v39, v127
	v_fmac_f32_e32 v88, v36, v128
	v_fmac_f32_e32 v90, v37, v129
	ds_read_b128 v[126:129], v143 offset:12896
	s_waitcnt lgkmcnt(11)
	v_fmac_f32_e32 v88, v34, v130
	v_fmac_f32_e32 v90, v35, v131
	v_fmac_f32_e32 v88, v32, v132
	v_fmac_f32_e32 v90, v33, v133
	ds_read_b128 v[130:133], v143 offset:12912
	s_waitcnt lgkmcnt(11)
	v_fmac_f32_e32 v88, v30, v134
	v_fmac_f32_e32 v90, v31, v135
	v_fmac_f32_e32 v88, v28, v136
	v_fmac_f32_e32 v90, v29, v137
	ds_read_b128 v[134:137], v143 offset:12928
	s_waitcnt lgkmcnt(11)
	v_fmac_f32_e32 v88, v26, v146
	v_fmac_f32_e32 v90, v27, v147
	v_fmac_f32_e32 v88, v24, v148
	v_fmac_f32_e32 v90, v25, v149
	ds_read_b128 v[146:149], v143 offset:12944
	s_waitcnt lgkmcnt(11)
; DI void gdn_g1(const Params& p, int l, int ch, char* smem) {
;     ...
;     for (int cc = 1; cc < 64; ++cc) { float a0 = 0.f, a1 = 0.f;
; #pragma unroll
;       for (int s2 = 0; s2 < cc; ++s2) { if (s2 & 1) a1 += sA[cc * 64 + s2] * sol[s2]; else a0 += sA[cc * 64 + s2] * sol[s2]; }
;       sol[cc] -= a0 + a1; }
	v_fmac_f32_e32 v88, v22, v150
	v_fmac_f32_e32 v90, v23, v151
	v_fmac_f32_e32 v88, v20, v152
	v_fmac_f32_e32 v90, v21, v153
	ds_read_b128 v[150:153], v143 offset:12960
	s_waitcnt lgkmcnt(11)
	v_fmac_f32_e32 v88, v18, v154
	v_add_f32_e32 v84, v90, v88
	v_sub_f32_e32 v19, v19, v84
	ds_read_b128 v[154:157], v143 offset:12976
	s_waitcnt lgkmcnt(11)
	v_fma_f32 v88, v4, v158, 0
	v_fma_f32 v90, v5, v159, 0
	v_fmac_f32_e32 v88, v80, v160
	v_fmac_f32_e32 v90, v81, v161
	ds_read_b64 v[158:159], v143 offset:12992
	s_waitcnt lgkmcnt(11)
	v_fmac_f32_e32 v88, v82, v162
	v_fmac_f32_e32 v90, v83, v163
	v_fmac_f32_e32 v88, v60, v164
	v_fmac_f32_e32 v90, v61, v165
	ds_read_b128 v[162:165], v143 offset:13056
	s_waitcnt lgkmcnt(11)
	v_fmac_f32_e32 v88, v58, v166
	v_fmac_f32_e32 v90, v59, v167
	v_fmac_f32_e32 v88, v56, v168
	v_fmac_f32_e32 v90, v57, v169
	ds_read_b128 v[166:169], v143 offset:13072
	s_waitcnt lgkmcnt(11)
	v_fmac_f32_e32 v88, v54, v114
	v_fmac_f32_e32 v90, v55, v115
	v_fmac_f32_e32 v88, v52, v116
	v_fmac_f32_e32 v90, v53, v117
	ds_read_b128 v[114:117], v143 offset:13088
	s_waitcnt lgkmcnt(11)
	v_fmac_f32_e32 v88, v50, v118
	v_fmac_f32_e32 v90, v51, v119
	v_fmac_f32_e32 v88, v48, v120
	v_fmac_f32_e32 v90, v49, v121
	ds_read_b128 v[118:121], v143 offset:13104
	s_waitcnt lgkmcnt(11)
	v_fmac_f32_e32 v88, v46, v122
	v_fmac_f32_e32 v90, v47, v123
	v_fmac_f32_e32 v88, v44, v124
	v_fmac_f32_e32 v90, v45, v125
	ds_read_b128 v[122:125], v143 offset:13120
	s_waitcnt lgkmcnt(11)
	v_fmac_f32_e32 v88, v42, v126
	v_fmac_f32_e32 v90, v43, v127
	v_fmac_f32_e32 v88, v40, v128
	v_fmac_f32_e32 v90, v41, v129
	ds_read_b128 v[126:129], v143 offset:13136
	s_waitcnt lgkmcnt(11)
	v_fmac_f32_e32 v88, v38, v130
	v_fmac_f32_e32 v90, v39, v131
	v_fmac_f32_e32 v88, v36, v132
	v_fmac_f32_e32 v90, v37, v133
	ds_read_b128 v[130:133], v143 offset:13152
	s_waitcnt lgkmcnt(11)
	v_fmac_f32_e32 v88, v34, v134
	v_fmac_f32_e32 v90, v35, v135
	v_fmac_f32_e32 v88, v32, v136
	v_fmac_f32_e32 v90, v33, v137
	ds_read_b128 v[134:137], v143 offset:13168
	s_waitcnt lgkmcnt(11)
	v_fmac_f32_e32 v88, v30, v146
	v_fmac_f32_e32 v90, v31, v147
	v_fmac_f32_e32 v88, v28, v148
	v_fmac_f32_e32 v90, v29, v149
	ds_read_b128 v[146:149], v143 offset:13184
	s_waitcnt lgkmcnt(11)
	v_fmac_f32_e32 v88, v26, v150
	v_fmac_f32_e32 v90, v27, v151
	v_fmac_f32_e32 v88, v24, v152
	v_fmac_f32_e32 v90, v25, v153
	ds_read_b128 v[150:153], v143 offset:13200
	s_waitcnt lgkmcnt(11)
	v_fmac_f32_e32 v88, v22, v154
	v_fmac_f32_e32 v90, v23, v155
	v_fmac_f32_e32 v88, v20, v156
	v_fmac_f32_e32 v90, v21, v157
	ds_read_b128 v[154:157], v143 offset:13216
	s_waitcnt lgkmcnt(11)
	v_fmac_f32_e32 v88, v18, v158
	v_fmac_f32_e32 v90, v19, v159
	v_add_f32_e32 v84, v88, v90
	v_sub_f32_e32 v16, v16, v84
	ds_read_b128 v[158:161], v143 offset:13232
	s_waitcnt lgkmcnt(11)
	v_fma_f32 v88, v4, v162, 0
	v_fma_f32 v90, v5, v163, 0
	v_fmac_f32_e32 v88, v80, v164
	v_fmac_f32_e32 v90, v81, v165
	ds_read_b96 v[162:164], v143 offset:13248
	s_waitcnt lgkmcnt(11)
	v_fmac_f32_e32 v88, v82, v166
	v_fmac_f32_e32 v90, v83, v167
	v_fmac_f32_e32 v88, v60, v168
	v_fmac_f32_e32 v90, v61, v169
	ds_read_b128 v[166:169], v143 offset:13312
	s_waitcnt lgkmcnt(11)
	v_fmac_f32_e32 v88, v58, v114
	v_fmac_f32_e32 v90, v59, v115
	v_fmac_f32_e32 v88, v56, v116
	v_fmac_f32_e32 v90, v57, v117
	ds_read_b128 v[114:117], v143 offset:13328
	s_waitcnt lgkmcnt(11)
	v_fmac_f32_e32 v88, v54, v118
	v_fmac_f32_e32 v90, v55, v119
	v_fmac_f32_e32 v88, v52, v120
	v_fmac_f32_e32 v90, v53, v121
	ds_read_b128 v[118:121], v143 offset:13344
	s_waitcnt lgkmcnt(11)
	v_fmac_f32_e32 v88, v50, v122
	v_fmac_f32_e32 v90, v51, v123
	v_fmac_f32_e32 v88, v48, v124
	v_fmac_f32_e32 v90, v49, v125
	ds_read_b128 v[122:125], v143 offset:13360
	s_waitcnt lgkmcnt(11)
	v_fmac_f32_e32 v88, v46, v126
	v_fmac_f32_e32 v90, v47, v127
	v_fmac_f32_e32 v88, v44, v128
	v_fmac_f32_e32 v90, v45, v129
	ds_read_b128 v[126:129], v143 offset:13376
	s_waitcnt lgkmcnt(11)
	v_fmac_f32_e32 v88, v42, v130
	v_fmac_f32_e32 v90, v43, v131
	v_fmac_f32_e32 v88, v40, v132
	v_fmac_f32_e32 v90, v41, v133
	ds_read_b128 v[130:133], v143 offset:13392
	s_waitcnt lgkmcnt(11)
	v_fmac_f32_e32 v88, v38, v134
	v_fmac_f32_e32 v90, v39, v135
	v_fmac_f32_e32 v88, v36, v136
	v_fmac_f32_e32 v90, v37, v137
	ds_read_b128 v[134:137], v143 offset:13408
	s_waitcnt lgkmcnt(11)
	v_fmac_f32_e32 v88, v34, v146
	v_fmac_f32_e32 v90, v35, v147
	v_fmac_f32_e32 v88, v32, v148
	v_fmac_f32_e32 v90, v33, v149
	ds_read_b128 v[146:149], v143 offset:13424
	s_waitcnt lgkmcnt(11)
	v_fmac_f32_e32 v88, v30, v150
	v_fmac_f32_e32 v90, v31, v151
	v_fmac_f32_e32 v88, v28, v152
	v_fmac_f32_e32 v90, v29, v153
	ds_read_b128 v[150:153], v143 offset:13440
	s_waitcnt lgkmcnt(11)
	v_fmac_f32_e32 v88, v26, v154
	v_fmac_f32_e32 v90, v27, v155
	v_fmac_f32_e32 v88, v24, v156
	v_fmac_f32_e32 v90, v25, v157
	ds_read_b128 v[154:157], v143 offset:13456
	s_waitcnt lgkmcnt(11)
	v_fmac_f32_e32 v88, v22, v158
	v_fmac_f32_e32 v90, v23, v159
	v_fmac_f32_e32 v88, v20, v160
	v_fmac_f32_e32 v90, v21, v161
	ds_read_b128 v[158:161], v143 offset:13472
	s_waitcnt lgkmcnt(11)
	v_fmac_f32_e32 v88, v18, v162
	v_fmac_f32_e32 v90, v19, v163
	v_fmac_f32_e32 v88, v16, v164
	v_add_f32_e32 v84, v90, v88
	v_sub_f32_e32 v17, v17, v84
	ds_read_b128 v[162:165], v143 offset:13488
	s_waitcnt lgkmcnt(11)
	v_fma_f32 v88, v4, v166, 0
	v_fma_f32 v90, v5, v167, 0
	v_fmac_f32_e32 v88, v80, v168
	v_fmac_f32_e32 v90, v81, v169
	ds_read_b128 v[166:169], v143 offset:13504
	s_waitcnt lgkmcnt(11)
	v_fmac_f32_e32 v88, v82, v114
	v_fmac_f32_e32 v90, v83, v115
	v_fmac_f32_e32 v88, v60, v116
	v_fmac_f32_e32 v90, v61, v117
	ds_read_b128 v[114:117], v143 offset:13568
	s_waitcnt lgkmcnt(11)
; DI void gdn_g1(const Params& p, int l, int ch, char* smem) {
;     ...
;     for (int cc = 1; cc < 64; ++cc) { float a0 = 0.f, a1 = 0.f;
; #pragma unroll
;       for (int s2 = 0; s2 < cc; ++s2) { if (s2 & 1) a1 += sA[cc * 64 + s2] * sol[s2]; else a0 += sA[cc * 64 + s2] * sol[s2]; }
;       sol[cc] -= a0 + a1; }
	v_fmac_f32_e32 v88, v58, v118
	v_fmac_f32_e32 v90, v59, v119
	v_fmac_f32_e32 v88, v56, v120
	v_fmac_f32_e32 v90, v57, v121
	ds_read_b128 v[118:121], v143 offset:13584
	s_waitcnt lgkmcnt(11)
	v_fmac_f32_e32 v88, v54, v122
	v_fmac_f32_e32 v90, v55, v123
	v_fmac_f32_e32 v88, v52, v124
	v_fmac_f32_e32 v90, v53, v125
	ds_read_b128 v[122:125], v143 offset:13600
	s_waitcnt lgkmcnt(11)
	v_fmac_f32_e32 v88, v50, v126
	v_fmac_f32_e32 v90, v51, v127
	v_fmac_f32_e32 v88, v48, v128
	v_fmac_f32_e32 v90, v49, v129
	ds_read_b128 v[126:129], v143 offset:13616
	s_waitcnt lgkmcnt(11)
	v_fmac_f32_e32 v88, v46, v130
	v_fmac_f32_e32 v90, v47, v131
	v_fmac_f32_e32 v88, v44, v132
	v_fmac_f32_e32 v90, v45, v133
	ds_read_b128 v[130:133], v143 offset:13632
	s_waitcnt lgkmcnt(11)
	v_fmac_f32_e32 v88, v42, v134
	v_fmac_f32_e32 v90, v43, v135
	v_fmac_f32_e32 v88, v40, v136
	v_fmac_f32_e32 v90, v41, v137
	ds_read_b128 v[134:137], v143 offset:13648
	s_waitcnt lgkmcnt(11)
	v_fmac_f32_e32 v88, v38, v146
	v_fmac_f32_e32 v90, v39, v147
	v_fmac_f32_e32 v88, v36, v148
	v_fmac_f32_e32 v90, v37, v149
	ds_read_b128 v[146:149], v143 offset:13664
	s_waitcnt lgkmcnt(11)
	v_fmac_f32_e32 v88, v34, v150
	v_fmac_f32_e32 v90, v35, v151
	v_fmac_f32_e32 v88, v32, v152
	v_fmac_f32_e32 v90, v33, v153
	ds_read_b128 v[150:153], v143 offset:13680
	s_waitcnt lgkmcnt(11)
	v_fmac_f32_e32 v88, v30, v154
	v_fmac_f32_e32 v90, v31, v155
	v_fmac_f32_e32 v88, v28, v156
	v_fmac_f32_e32 v90, v29, v157
	ds_read_b128 v[154:157], v143 offset:13696
	s_waitcnt lgkmcnt(11)
	v_fmac_f32_e32 v88, v26, v158
	v_fmac_f32_e32 v90, v27, v159
	v_fmac_f32_e32 v88, v24, v160
	v_fmac_f32_e32 v90, v25, v161
	ds_read_b128 v[158:161], v143 offset:13712
	s_waitcnt lgkmcnt(11)
	v_fmac_f32_e32 v88, v22, v162
	v_fmac_f32_e32 v90, v23, v163
	v_fmac_f32_e32 v88, v20, v164
	v_fmac_f32_e32 v90, v21, v165
	ds_read_b128 v[162:165], v143 offset:13728
	s_waitcnt lgkmcnt(11)
	v_fmac_f32_e32 v88, v18, v166
	v_fmac_f32_e32 v90, v19, v167
	v_fmac_f32_e32 v88, v16, v168
	v_fmac_f32_e32 v90, v17, v169
	v_add_f32_e32 v84, v88, v90
	v_sub_f32_e32 v14, v14, v84
	ds_read_b128 v[166:169], v143 offset:13744
	s_waitcnt lgkmcnt(11)
	v_fma_f32 v88, v4, v114, 0
	v_fma_f32 v90, v5, v115, 0
	v_fmac_f32_e32 v88, v80, v116
	v_fmac_f32_e32 v90, v81, v117
	ds_read_b128 v[114:117], v143 offset:13760
	s_waitcnt lgkmcnt(11)
	v_fmac_f32_e32 v88, v82, v118
	v_fmac_f32_e32 v90, v83, v119
	v_fmac_f32_e32 v88, v60, v120
	v_fmac_f32_e32 v90, v61, v121
	ds_read_b32 v118, v143 offset:13776
	s_waitcnt lgkmcnt(11)
	v_fmac_f32_e32 v88, v58, v122
	v_fmac_f32_e32 v90, v59, v123
	v_fmac_f32_e32 v88, v56, v124
	v_fmac_f32_e32 v90, v57, v125
	ds_read_b128 v[122:125], v143 offset:13824
	s_waitcnt lgkmcnt(11)
	v_fmac_f32_e32 v88, v54, v126
	v_fmac_f32_e32 v90, v55, v127
	v_fmac_f32_e32 v88, v52, v128
	v_fmac_f32_e32 v90, v53, v129
	ds_read_b128 v[126:129], v143 offset:13840
	s_waitcnt lgkmcnt(11)
	v_fmac_f32_e32 v88, v50, v130
	v_fmac_f32_e32 v90, v51, v131
	v_fmac_f32_e32 v88, v48, v132
	v_fmac_f32_e32 v90, v49, v133
	ds_read_b128 v[130:133], v143 offset:13856
	s_waitcnt lgkmcnt(11)
	v_fmac_f32_e32 v88, v46, v134
	v_fmac_f32_e32 v90, v47, v135
	v_fmac_f32_e32 v88, v44, v136
	v_fmac_f32_e32 v90, v45, v137
	ds_read_b128 v[134:137], v143 offset:13872
	s_waitcnt lgkmcnt(11)
	v_fmac_f32_e32 v88, v42, v146
	v_fmac_f32_e32 v90, v43, v147
	v_fmac_f32_e32 v88, v40, v148
	v_fmac_f32_e32 v90, v41, v149
	ds_read_b128 v[146:149], v143 offset:13888
	s_waitcnt lgkmcnt(11)
	v_fmac_f32_e32 v88, v38, v150
	v_fmac_f32_e32 v90, v39, v151
	v_fmac_f32_e32 v88, v36, v152
	v_fmac_f32_e32 v90, v37, v153
	ds_read_b128 v[150:153], v143 offset:13904
	s_waitcnt lgkmcnt(11)
	v_fmac_f32_e32 v88, v34, v154
	v_fmac_f32_e32 v90, v35, v155
	v_fmac_f32_e32 v88, v32, v156
	v_fmac_f32_e32 v90, v33, v157
	ds_read_b128 v[154:157], v143 offset:13920
	s_waitcnt lgkmcnt(11)
	v_fmac_f32_e32 v88, v30, v158
	v_fmac_f32_e32 v90, v31, v159
	v_fmac_f32_e32 v88, v28, v160
	v_fmac_f32_e32 v90, v29, v161
	ds_read_b128 v[158:161], v143 offset:13936
	s_waitcnt lgkmcnt(11)
	v_fmac_f32_e32 v88, v26, v162
	v_fmac_f32_e32 v90, v27, v163
	v_fmac_f32_e32 v88, v24, v164
	v_fmac_f32_e32 v90, v25, v165
	ds_read_b128 v[162:165], v143 offset:13952
	s_waitcnt lgkmcnt(11)
	v_fmac_f32_e32 v88, v22, v166
	v_fmac_f32_e32 v90, v23, v167
	v_fmac_f32_e32 v88, v20, v168
	v_fmac_f32_e32 v90, v21, v169
	ds_read_b128 v[166:169], v143 offset:13968
	s_waitcnt lgkmcnt(11)
	v_fmac_f32_e32 v88, v18, v114
	v_fmac_f32_e32 v90, v19, v115
	v_fmac_f32_e32 v88, v16, v116
	v_fmac_f32_e32 v90, v17, v117
	ds_read_b128 v[114:117], v143 offset:13984
	s_waitcnt lgkmcnt(11)
	v_fmac_f32_e32 v88, v14, v118
	v_add_f32_e32 v84, v90, v88
	v_sub_f32_e32 v15, v15, v84
	ds_read_b128 v[118:121], v143 offset:14000
	s_waitcnt lgkmcnt(11)
	v_fma_f32 v88, v4, v122, 0
	v_fma_f32 v90, v5, v123, 0
	v_fmac_f32_e32 v88, v80, v124
	v_fmac_f32_e32 v90, v81, v125
	ds_read_b128 v[122:125], v143 offset:14016
	s_waitcnt lgkmcnt(11)
	v_fmac_f32_e32 v88, v82, v126
	v_fmac_f32_e32 v90, v83, v127
	v_fmac_f32_e32 v88, v60, v128
	v_fmac_f32_e32 v90, v61, v129
	ds_read_b64 v[126:127], v143 offset:14032
	s_waitcnt lgkmcnt(11)
	v_fmac_f32_e32 v88, v58, v130
	v_fmac_f32_e32 v90, v59, v131
	v_fmac_f32_e32 v88, v56, v132
	v_fmac_f32_e32 v90, v57, v133
	ds_read_b128 v[130:133], v143 offset:14080
	s_waitcnt lgkmcnt(11)
	v_fmac_f32_e32 v88, v54, v134
	v_fmac_f32_e32 v90, v55, v135
	v_fmac_f32_e32 v88, v52, v136
	v_fmac_f32_e32 v90, v53, v137
	ds_read_b128 v[134:137], v143 offset:14096
	s_waitcnt lgkmcnt(11)
	v_fmac_f32_e32 v88, v50, v146
	v_fmac_f32_e32 v90, v51, v147
	v_fmac_f32_e32 v88, v48, v148
	v_fmac_f32_e32 v90, v49, v149
	ds_read_b128 v[146:149], v143 offset:14112
	s_waitcnt lgkmcnt(11)
; DI void gdn_g1(const Params& p, int l, int ch, char* smem) {
;     ...
;     for (int cc = 1; cc < 64; ++cc) { float a0 = 0.f, a1 = 0.f;
; #pragma unroll
;       for (int s2 = 0; s2 < cc; ++s2) { if (s2 & 1) a1 += sA[cc * 64 + s2] * sol[s2]; else a0 += sA[cc * 64 + s2] * sol[s2]; }
;       sol[cc] -= a0 + a1; }
	v_fmac_f32_e32 v88, v46, v150
	v_fmac_f32_e32 v90, v47, v151
	v_fmac_f32_e32 v88, v44, v152
	v_fmac_f32_e32 v90, v45, v153
	ds_read_b128 v[150:153], v143 offset:14128
	s_waitcnt lgkmcnt(11)
	v_fmac_f32_e32 v88, v42, v154
	v_fmac_f32_e32 v90, v43, v155
	v_fmac_f32_e32 v88, v40, v156
	v_fmac_f32_e32 v90, v41, v157
	ds_read_b128 v[154:157], v143 offset:14144
	s_waitcnt lgkmcnt(11)
	v_fmac_f32_e32 v88, v38, v158
	v_fmac_f32_e32 v90, v39, v159
	v_fmac_f32_e32 v88, v36, v160
	v_fmac_f32_e32 v90, v37, v161
	ds_read_b128 v[158:161], v143 offset:14160
	s_waitcnt lgkmcnt(11)
	v_fmac_f32_e32 v88, v34, v162
	v_fmac_f32_e32 v90, v35, v163
	v_fmac_f32_e32 v88, v32, v164
	v_fmac_f32_e32 v90, v33, v165
	ds_read_b128 v[162:165], v143 offset:14176
	s_waitcnt lgkmcnt(11)
	v_fmac_f32_e32 v88, v30, v166
	v_fmac_f32_e32 v90, v31, v167
	v_fmac_f32_e32 v88, v28, v168
	v_fmac_f32_e32 v90, v29, v169
	ds_read_b128 v[166:169], v143 offset:14192
	s_waitcnt lgkmcnt(11)
	v_fmac_f32_e32 v88, v26, v114
	v_fmac_f32_e32 v90, v27, v115
	v_fmac_f32_e32 v88, v24, v116
	v_fmac_f32_e32 v90, v25, v117
	ds_read_b128 v[114:117], v143 offset:14208
	s_waitcnt lgkmcnt(11)
	v_fmac_f32_e32 v88, v22, v118
	v_fmac_f32_e32 v90, v23, v119
	v_fmac_f32_e32 v88, v20, v120
	v_fmac_f32_e32 v90, v21, v121
	ds_read_b128 v[118:121], v143 offset:14224
	s_waitcnt lgkmcnt(11)
	v_fmac_f32_e32 v88, v18, v122
	v_fmac_f32_e32 v90, v19, v123
	v_fmac_f32_e32 v88, v16, v124
	v_fmac_f32_e32 v90, v17, v125
	ds_read_b128 v[122:125], v143 offset:14240
	s_waitcnt lgkmcnt(11)
	v_fmac_f32_e32 v88, v14, v126
	v_fmac_f32_e32 v90, v15, v127
	v_add_f32_e32 v84, v88, v90
	v_sub_f32_e32 v12, v12, v84
	ds_read_b128 v[126:129], v143 offset:14256
	s_waitcnt lgkmcnt(11)
	v_fma_f32 v88, v4, v130, 0
	v_fma_f32 v90, v5, v131, 0
	v_fmac_f32_e32 v88, v80, v132
	v_fmac_f32_e32 v90, v81, v133
	ds_read_b128 v[130:133], v143 offset:14272
	s_waitcnt lgkmcnt(11)
	v_fmac_f32_e32 v88, v82, v134
	v_fmac_f32_e32 v90, v83, v135
	v_fmac_f32_e32 v88, v60, v136
	v_fmac_f32_e32 v90, v61, v137
	ds_read_b96 v[134:136], v143 offset:14288
	s_waitcnt lgkmcnt(11)
	v_fmac_f32_e32 v88, v58, v146
	v_fmac_f32_e32 v90, v59, v147
	v_fmac_f32_e32 v88, v56, v148
	v_fmac_f32_e32 v90, v57, v149
	ds_read_b128 v[146:149], v143 offset:14336
	s_waitcnt lgkmcnt(11)
	v_fmac_f32_e32 v88, v54, v150
	v_fmac_f32_e32 v90, v55, v151
	v_fmac_f32_e32 v88, v52, v152
	v_fmac_f32_e32 v90, v53, v153
	ds_read_b128 v[150:153], v143 offset:14352
	s_waitcnt lgkmcnt(11)
	v_fmac_f32_e32 v88, v50, v154
	v_fmac_f32_e32 v90, v51, v155
	v_fmac_f32_e32 v88, v48, v156
	v_fmac_f32_e32 v90, v49, v157
	ds_read_b128 v[154:157], v143 offset:14368
	s_waitcnt lgkmcnt(11)
	v_fmac_f32_e32 v88, v46, v158
	v_fmac_f32_e32 v90, v47, v159
	v_fmac_f32_e32 v88, v44, v160
	v_fmac_f32_e32 v90, v45, v161
	ds_read_b128 v[158:161], v143 offset:14384
	s_waitcnt lgkmcnt(11)
	v_fmac_f32_e32 v88, v42, v162
	v_fmac_f32_e32 v90, v43, v163
	v_fmac_f32_e32 v88, v40, v164
	v_fmac_f32_e32 v90, v41, v165
	ds_read_b128 v[162:165], v143 offset:14400
	s_waitcnt lgkmcnt(11)
	v_fmac_f32_e32 v88, v38, v166
	v_fmac_f32_e32 v90, v39, v167
	v_fmac_f32_e32 v88, v36, v168
	v_fmac_f32_e32 v90, v37, v169
	ds_read_b128 v[166:169], v143 offset:14416
	s_waitcnt lgkmcnt(11)
	v_fmac_f32_e32 v88, v34, v114
	v_fmac_f32_e32 v90, v35, v115
	v_fmac_f32_e32 v88, v32, v116
	v_fmac_f32_e32 v90, v33, v117
	ds_read_b128 v[114:117], v143 offset:14432
	s_waitcnt lgkmcnt(11)
	v_fmac_f32_e32 v88, v30, v118
	v_fmac_f32_e32 v90, v31, v119
	v_fmac_f32_e32 v88, v28, v120
	v_fmac_f32_e32 v90, v29, v121
	ds_read_b128 v[118:121], v143 offset:14448
	s_waitcnt lgkmcnt(11)
	v_fmac_f32_e32 v88, v26, v122
	v_fmac_f32_e32 v90, v27, v123
	v_fmac_f32_e32 v88, v24, v124
	v_fmac_f32_e32 v90, v25, v125
	ds_read_b128 v[122:125], v143 offset:14464
	s_waitcnt lgkmcnt(11)
	v_fmac_f32_e32 v88, v22, v126
	v_fmac_f32_e32 v90, v23, v127
	v_fmac_f32_e32 v88, v20, v128
	v_fmac_f32_e32 v90, v21, v129
	ds_read_b128 v[126:129], v143 offset:14480
	s_waitcnt lgkmcnt(11)
	v_fmac_f32_e32 v88, v18, v130
	v_fmac_f32_e32 v90, v19, v131
	v_fmac_f32_e32 v88, v16, v132
	v_fmac_f32_e32 v90, v17, v133
	ds_read_b128 v[130:133], v143 offset:14496
	s_waitcnt lgkmcnt(11)
	v_fmac_f32_e32 v88, v14, v134
	v_fmac_f32_e32 v90, v15, v135
	v_fmac_f32_e32 v88, v12, v136
	v_add_f32_e32 v84, v90, v88
	v_sub_f32_e32 v13, v13, v84
	ds_read_b128 v[134:137], v143 offset:14512
	s_waitcnt lgkmcnt(11)
	v_fma_f32 v88, v4, v146, 0
	v_fma_f32 v90, v5, v147, 0
	v_fmac_f32_e32 v88, v80, v148
	v_fmac_f32_e32 v90, v81, v149
	ds_read_b128 v[146:149], v143 offset:14528
	s_waitcnt lgkmcnt(11)
	v_fmac_f32_e32 v88, v82, v150
	v_fmac_f32_e32 v90, v83, v151
	v_fmac_f32_e32 v88, v60, v152
	v_fmac_f32_e32 v90, v61, v153
	ds_read_b128 v[150:153], v143 offset:14544
	s_waitcnt lgkmcnt(11)
	v_fmac_f32_e32 v88, v58, v154
	v_fmac_f32_e32 v90, v59, v155
	v_fmac_f32_e32 v88, v56, v156
	v_fmac_f32_e32 v90, v57, v157
	ds_read_b128 v[154:157], v143 offset:14592
	s_waitcnt lgkmcnt(11)
	v_fmac_f32_e32 v88, v54, v158
	v_fmac_f32_e32 v90, v55, v159
	v_fmac_f32_e32 v88, v52, v160
	v_fmac_f32_e32 v90, v53, v161
	ds_read_b128 v[158:161], v143 offset:14608
	s_waitcnt lgkmcnt(11)
	v_fmac_f32_e32 v88, v50, v162
	v_fmac_f32_e32 v90, v51, v163
	v_fmac_f32_e32 v88, v48, v164
	v_fmac_f32_e32 v90, v49, v165
	ds_read_b128 v[162:165], v143 offset:14624
	s_waitcnt lgkmcnt(11)
	v_fmac_f32_e32 v88, v46, v166
	v_fmac_f32_e32 v90, v47, v167
	v_fmac_f32_e32 v88, v44, v168
	v_fmac_f32_e32 v90, v45, v169
	ds_read_b128 v[166:169], v143 offset:14640
	s_waitcnt lgkmcnt(11)
; DI void gdn_g1(const Params& p, int l, int ch, char* smem) {
;     ...
;     for (int cc = 1; cc < 64; ++cc) { float a0 = 0.f, a1 = 0.f;
; #pragma unroll
;       for (int s2 = 0; s2 < cc; ++s2) { if (s2 & 1) a1 += sA[cc * 64 + s2] * sol[s2]; else a0 += sA[cc * 64 + s2] * sol[s2]; }
;       sol[cc] -= a0 + a1; }
	v_fmac_f32_e32 v88, v42, v114
	v_fmac_f32_e32 v90, v43, v115
	v_fmac_f32_e32 v88, v40, v116
	v_fmac_f32_e32 v90, v41, v117
	ds_read_b128 v[114:117], v143 offset:14656
	s_waitcnt lgkmcnt(11)
	v_fmac_f32_e32 v88, v38, v118
	v_fmac_f32_e32 v90, v39, v119
	v_fmac_f32_e32 v88, v36, v120
	v_fmac_f32_e32 v90, v37, v121
	ds_read_b128 v[118:121], v143 offset:14672
	s_waitcnt lgkmcnt(11)
	v_fmac_f32_e32 v88, v34, v122
	v_fmac_f32_e32 v90, v35, v123
	v_fmac_f32_e32 v88, v32, v124
	v_fmac_f32_e32 v90, v33, v125
	ds_read_b128 v[122:125], v143 offset:14688
	s_waitcnt lgkmcnt(11)
	v_fmac_f32_e32 v88, v30, v126
	v_fmac_f32_e32 v90, v31, v127
	v_fmac_f32_e32 v88, v28, v128
	v_fmac_f32_e32 v90, v29, v129
	ds_read_b128 v[126:129], v143 offset:14704
	s_waitcnt lgkmcnt(11)
	v_fmac_f32_e32 v88, v26, v130
	v_fmac_f32_e32 v90, v27, v131
	v_fmac_f32_e32 v88, v24, v132
	v_fmac_f32_e32 v90, v25, v133
	ds_read_b128 v[130:133], v143 offset:14720
	s_waitcnt lgkmcnt(11)
	v_fmac_f32_e32 v88, v22, v134
	v_fmac_f32_e32 v90, v23, v135
	v_fmac_f32_e32 v88, v20, v136
	v_fmac_f32_e32 v90, v21, v137
	ds_read_b128 v[134:137], v143 offset:14736
	s_waitcnt lgkmcnt(11)
	v_fmac_f32_e32 v88, v18, v146
	v_fmac_f32_e32 v90, v19, v147
	v_fmac_f32_e32 v88, v16, v148
	v_fmac_f32_e32 v90, v17, v149
	ds_read_b128 v[146:149], v143 offset:14752
	s_waitcnt lgkmcnt(11)
	v_fmac_f32_e32 v88, v14, v150
	v_fmac_f32_e32 v90, v15, v151
	v_fmac_f32_e32 v88, v12, v152
	v_fmac_f32_e32 v90, v13, v153
	v_add_f32_e32 v84, v88, v90
	v_sub_f32_e32 v10, v10, v84
	ds_read_b128 v[150:153], v143 offset:14768
	s_waitcnt lgkmcnt(11)
	v_fma_f32 v88, v4, v154, 0
	v_fma_f32 v90, v5, v155, 0
	v_fmac_f32_e32 v88, v80, v156
	v_fmac_f32_e32 v90, v81, v157
	ds_read_b128 v[154:157], v143 offset:14784
	s_waitcnt lgkmcnt(11)
	v_fmac_f32_e32 v88, v82, v158
	v_fmac_f32_e32 v90, v83, v159
	v_fmac_f32_e32 v88, v60, v160
	v_fmac_f32_e32 v90, v61, v161
	ds_read_b128 v[158:161], v143 offset:14800
	s_waitcnt lgkmcnt(11)
	v_fmac_f32_e32 v88, v58, v162
	v_fmac_f32_e32 v90, v59, v163
	v_fmac_f32_e32 v88, v56, v164
	v_fmac_f32_e32 v90, v57, v165
	ds_read_b32 v162, v143 offset:14816
	s_waitcnt lgkmcnt(11)
	v_fmac_f32_e32 v88, v54, v166
	v_fmac_f32_e32 v90, v55, v167
	v_fmac_f32_e32 v88, v52, v168
	v_fmac_f32_e32 v90, v53, v169
	ds_read_b128 v[166:169], v143 offset:14848
	s_waitcnt lgkmcnt(11)
	v_fmac_f32_e32 v88, v50, v114
	v_fmac_f32_e32 v90, v51, v115
	v_fmac_f32_e32 v88, v48, v116
	v_fmac_f32_e32 v90, v49, v117
	ds_read_b128 v[114:117], v143 offset:14864
	s_waitcnt lgkmcnt(11)
	v_fmac_f32_e32 v88, v46, v118
	v_fmac_f32_e32 v90, v47, v119
	v_fmac_f32_e32 v88, v44, v120
	v_fmac_f32_e32 v90, v45, v121
	ds_read_b128 v[118:121], v143 offset:14880
	s_waitcnt lgkmcnt(11)
	v_fmac_f32_e32 v88, v42, v122
	v_fmac_f32_e32 v90, v43, v123
	v_fmac_f32_e32 v88, v40, v124
	v_fmac_f32_e32 v90, v41, v125
	ds_read_b128 v[122:125], v143 offset:14896
	s_waitcnt lgkmcnt(11)
	v_fmac_f32_e32 v88, v38, v126
	v_fmac_f32_e32 v90, v39, v127
	v_fmac_f32_e32 v88, v36, v128
	v_fmac_f32_e32 v90, v37, v129
	ds_read_b128 v[126:129], v143 offset:14912
	s_waitcnt lgkmcnt(11)
	v_fmac_f32_e32 v88, v34, v130
	v_fmac_f32_e32 v90, v35, v131
	v_fmac_f32_e32 v88, v32, v132
	v_fmac_f32_e32 v90, v33, v133
	ds_read_b128 v[130:133], v143 offset:14928
	s_waitcnt lgkmcnt(11)
	v_fmac_f32_e32 v88, v30, v134
	v_fmac_f32_e32 v90, v31, v135
	v_fmac_f32_e32 v88, v28, v136
	v_fmac_f32_e32 v90, v29, v137
	ds_read_b128 v[134:137], v143 offset:14944
	s_waitcnt lgkmcnt(11)
	v_fmac_f32_e32 v88, v26, v146
	v_fmac_f32_e32 v90, v27, v147
	v_fmac_f32_e32 v88, v24, v148
	v_fmac_f32_e32 v90, v25, v149
	ds_read_b128 v[146:149], v143 offset:14960
	s_waitcnt lgkmcnt(11)
	v_fmac_f32_e32 v88, v22, v150
	v_fmac_f32_e32 v90, v23, v151
	v_fmac_f32_e32 v88, v20, v152
	v_fmac_f32_e32 v90, v21, v153
	ds_read_b128 v[150:153], v143 offset:14976
	s_waitcnt lgkmcnt(11)
	v_fmac_f32_e32 v88, v18, v154
	v_fmac_f32_e32 v90, v19, v155
	v_fmac_f32_e32 v88, v16, v156
	v_fmac_f32_e32 v90, v17, v157
	ds_read_b128 v[154:157], v143 offset:14992
	s_waitcnt lgkmcnt(11)
	v_fmac_f32_e32 v88, v14, v158
	v_fmac_f32_e32 v90, v15, v159
	v_fmac_f32_e32 v88, v12, v160
	v_fmac_f32_e32 v90, v13, v161
	ds_read_b128 v[158:161], v143 offset:15008
	s_waitcnt lgkmcnt(11)
	v_fmac_f32_e32 v88, v10, v162
	v_add_f32_e32 v84, v90, v88
	v_sub_f32_e32 v11, v11, v84
	ds_read_b128 v[162:165], v143 offset:15024
	s_waitcnt lgkmcnt(11)
	v_fma_f32 v88, v4, v166, 0
	v_fma_f32 v90, v5, v167, 0
	v_fmac_f32_e32 v88, v80, v168
	v_fmac_f32_e32 v90, v81, v169
	ds_read_b128 v[166:169], v143 offset:15040
	s_waitcnt lgkmcnt(11)
	v_fmac_f32_e32 v88, v82, v114
	v_fmac_f32_e32 v90, v83, v115
	v_fmac_f32_e32 v88, v60, v116
	v_fmac_f32_e32 v90, v61, v117
	ds_read_b128 v[114:117], v143 offset:15056
	s_waitcnt lgkmcnt(11)
	v_fmac_f32_e32 v88, v58, v118
	v_fmac_f32_e32 v90, v59, v119
	v_fmac_f32_e32 v88, v56, v120
	v_fmac_f32_e32 v90, v57, v121
	ds_read_b64 v[118:119], v143 offset:15072
	s_waitcnt lgkmcnt(11)
	v_fmac_f32_e32 v88, v54, v122
	v_fmac_f32_e32 v90, v55, v123
	v_fmac_f32_e32 v88, v52, v124
	v_fmac_f32_e32 v90, v53, v125
	ds_read_b128 v[122:125], v143 offset:15104
	s_waitcnt lgkmcnt(11)
	v_fmac_f32_e32 v88, v50, v126
	v_fmac_f32_e32 v90, v51, v127
	v_fmac_f32_e32 v88, v48, v128
	v_fmac_f32_e32 v90, v49, v129
	ds_read_b128 v[126:129], v143 offset:15120
	s_waitcnt lgkmcnt(11)
	v_fmac_f32_e32 v88, v46, v130
	v_fmac_f32_e32 v90, v47, v131
	v_fmac_f32_e32 v88, v44, v132
	v_fmac_f32_e32 v90, v45, v133
	ds_read_b128 v[130:133], v143 offset:15136
	s_waitcnt lgkmcnt(11)
	v_fmac_f32_e32 v88, v42, v134
	v_fmac_f32_e32 v90, v43, v135
	v_fmac_f32_e32 v88, v40, v136
	v_fmac_f32_e32 v90, v41, v137
	ds_read_b128 v[134:137], v143 offset:15152
	s_waitcnt lgkmcnt(11)
; DI void gdn_g1(const Params& p, int l, int ch, char* smem) {
;     ...
;     for (int cc = 1; cc < 64; ++cc) { float a0 = 0.f, a1 = 0.f;
; #pragma unroll
;       for (int s2 = 0; s2 < cc; ++s2) { if (s2 & 1) a1 += sA[cc * 64 + s2] * sol[s2]; else a0 += sA[cc * 64 + s2] * sol[s2]; }
;       sol[cc] -= a0 + a1; }
	v_fmac_f32_e32 v88, v38, v146
	v_fmac_f32_e32 v90, v39, v147
	v_fmac_f32_e32 v88, v36, v148
	v_fmac_f32_e32 v90, v37, v149
	ds_read_b128 v[146:149], v143 offset:15168
	s_waitcnt lgkmcnt(11)
	v_fmac_f32_e32 v88, v34, v150
	v_fmac_f32_e32 v90, v35, v151
	v_fmac_f32_e32 v88, v32, v152
	v_fmac_f32_e32 v90, v33, v153
	ds_read_b128 v[150:153], v143 offset:15184
	s_waitcnt lgkmcnt(11)
	v_fmac_f32_e32 v88, v30, v154
	v_fmac_f32_e32 v90, v31, v155
	v_fmac_f32_e32 v88, v28, v156
	v_fmac_f32_e32 v90, v29, v157
	ds_read_b128 v[154:157], v143 offset:15200
	s_waitcnt lgkmcnt(11)
	v_fmac_f32_e32 v88, v26, v158
	v_fmac_f32_e32 v90, v27, v159
	v_fmac_f32_e32 v88, v24, v160
	v_fmac_f32_e32 v90, v25, v161
	ds_read_b128 v[158:161], v143 offset:15216
	s_waitcnt lgkmcnt(11)
	v_fmac_f32_e32 v88, v22, v162
	v_fmac_f32_e32 v90, v23, v163
	v_fmac_f32_e32 v88, v20, v164
	v_fmac_f32_e32 v90, v21, v165
	ds_read_b128 v[162:165], v143 offset:15232
	s_waitcnt lgkmcnt(11)
	v_fmac_f32_e32 v88, v18, v166
	v_fmac_f32_e32 v90, v19, v167
	v_fmac_f32_e32 v88, v16, v168
	v_fmac_f32_e32 v90, v17, v169
	ds_read_b128 v[166:169], v143 offset:15248
	s_waitcnt lgkmcnt(11)
	v_fmac_f32_e32 v88, v14, v114
	v_fmac_f32_e32 v90, v15, v115
	v_fmac_f32_e32 v88, v12, v116
	v_fmac_f32_e32 v90, v13, v117
	ds_read_b128 v[114:117], v143 offset:15264
	s_waitcnt lgkmcnt(11)
	v_fmac_f32_e32 v88, v10, v118
	v_fmac_f32_e32 v90, v11, v119
	v_add_f32_e32 v84, v88, v90
	v_sub_f32_e32 v8, v8, v84
	ds_read_b128 v[118:121], v143 offset:15280
	s_waitcnt lgkmcnt(11)
	v_fma_f32 v88, v4, v122, 0
	v_fma_f32 v90, v5, v123, 0
	v_fmac_f32_e32 v88, v80, v124
	v_fmac_f32_e32 v90, v81, v125
	ds_read_b128 v[122:125], v143 offset:15296
	s_waitcnt lgkmcnt(11)
	v_fmac_f32_e32 v88, v82, v126
	v_fmac_f32_e32 v90, v83, v127
	v_fmac_f32_e32 v88, v60, v128
	v_fmac_f32_e32 v90, v61, v129
	ds_read_b128 v[126:129], v143 offset:15312
	s_waitcnt lgkmcnt(11)
	v_fmac_f32_e32 v88, v58, v130
	v_fmac_f32_e32 v90, v59, v131
	v_fmac_f32_e32 v88, v56, v132
	v_fmac_f32_e32 v90, v57, v133
	ds_read_b96 v[130:132], v143 offset:15328
	s_waitcnt lgkmcnt(11)
	v_fmac_f32_e32 v88, v54, v134
	v_fmac_f32_e32 v90, v55, v135
	v_fmac_f32_e32 v88, v52, v136
	v_fmac_f32_e32 v90, v53, v137
	ds_read_b128 v[134:137], v143 offset:15360
	s_waitcnt lgkmcnt(11)
	v_fmac_f32_e32 v88, v50, v146
	v_fmac_f32_e32 v90, v51, v147
	v_fmac_f32_e32 v88, v48, v148
	v_fmac_f32_e32 v90, v49, v149
	ds_read_b128 v[146:149], v143 offset:15376
	s_waitcnt lgkmcnt(11)
	v_fmac_f32_e32 v88, v46, v150
	v_fmac_f32_e32 v90, v47, v151
	v_fmac_f32_e32 v88, v44, v152
	v_fmac_f32_e32 v90, v45, v153
	ds_read_b128 v[150:153], v143 offset:15392
	s_waitcnt lgkmcnt(11)
	v_fmac_f32_e32 v88, v42, v154
	v_fmac_f32_e32 v90, v43, v155
	v_fmac_f32_e32 v88, v40, v156
	v_fmac_f32_e32 v90, v41, v157
	ds_read_b128 v[154:157], v143 offset:15408
	s_waitcnt lgkmcnt(11)
	v_fmac_f32_e32 v88, v38, v158
	v_fmac_f32_e32 v90, v39, v159
	v_fmac_f32_e32 v88, v36, v160
	v_fmac_f32_e32 v90, v37, v161
	ds_read_b128 v[158:161], v143 offset:15424
	s_waitcnt lgkmcnt(11)
	v_fmac_f32_e32 v88, v34, v162
	v_fmac_f32_e32 v90, v35, v163
	v_fmac_f32_e32 v88, v32, v164
	v_fmac_f32_e32 v90, v33, v165
	ds_read_b128 v[162:165], v143 offset:15440
	s_waitcnt lgkmcnt(11)
	v_fmac_f32_e32 v88, v30, v166
	v_fmac_f32_e32 v90, v31, v167
	v_fmac_f32_e32 v88, v28, v168
	v_fmac_f32_e32 v90, v29, v169
	ds_read_b128 v[166:169], v143 offset:15456
	s_waitcnt lgkmcnt(11)
	v_fmac_f32_e32 v88, v26, v114
	v_fmac_f32_e32 v90, v27, v115
	v_fmac_f32_e32 v88, v24, v116
	v_fmac_f32_e32 v90, v25, v117
	ds_read_b128 v[114:117], v143 offset:15472
	s_waitcnt lgkmcnt(11)
	v_fmac_f32_e32 v88, v22, v118
	v_fmac_f32_e32 v90, v23, v119
	v_fmac_f32_e32 v88, v20, v120
	v_fmac_f32_e32 v90, v21, v121
	ds_read_b128 v[118:121], v143 offset:15488
	s_waitcnt lgkmcnt(11)
	v_fmac_f32_e32 v88, v18, v122
	v_fmac_f32_e32 v90, v19, v123
	v_fmac_f32_e32 v88, v16, v124
	v_fmac_f32_e32 v90, v17, v125
	ds_read_b128 v[122:125], v143 offset:15504
	s_waitcnt lgkmcnt(11)
	v_fmac_f32_e32 v88, v14, v126
	v_fmac_f32_e32 v90, v15, v127
	v_fmac_f32_e32 v88, v12, v128
	v_fmac_f32_e32 v90, v13, v129
	ds_read_b128 v[126:129], v143 offset:15520
	s_waitcnt lgkmcnt(11)
	v_fmac_f32_e32 v88, v10, v130
	v_fmac_f32_e32 v90, v11, v131
	v_fmac_f32_e32 v88, v8, v132
	v_add_f32_e32 v84, v90, v88
	v_sub_f32_e32 v9, v9, v84
	ds_read_b128 v[130:133], v143 offset:15536
	s_waitcnt lgkmcnt(11)
	v_fma_f32 v88, v4, v134, 0
	v_fma_f32 v90, v5, v135, 0
	v_fmac_f32_e32 v88, v80, v136
	v_fmac_f32_e32 v90, v81, v137
	ds_read_b128 v[134:137], v143 offset:15552
	s_waitcnt lgkmcnt(11)
	v_fmac_f32_e32 v88, v82, v146
	v_fmac_f32_e32 v90, v83, v147
	v_fmac_f32_e32 v88, v60, v148
	v_fmac_f32_e32 v90, v61, v149
	ds_read_b128 v[146:149], v143 offset:15568
	s_waitcnt lgkmcnt(11)
	v_fmac_f32_e32 v88, v58, v150
	v_fmac_f32_e32 v90, v59, v151
	v_fmac_f32_e32 v88, v56, v152
	v_fmac_f32_e32 v90, v57, v153
	ds_read_b128 v[150:153], v143 offset:15584
	s_waitcnt lgkmcnt(11)
	v_fmac_f32_e32 v88, v54, v154
	v_fmac_f32_e32 v90, v55, v155
	v_fmac_f32_e32 v88, v52, v156
	v_fmac_f32_e32 v90, v53, v157
	ds_read_b128 v[154:157], v143 offset:15616
	s_waitcnt lgkmcnt(11)
	v_fmac_f32_e32 v88, v50, v158
	v_fmac_f32_e32 v90, v51, v159
	v_fmac_f32_e32 v88, v48, v160
	v_fmac_f32_e32 v90, v49, v161
	ds_read_b128 v[158:161], v143 offset:15632
	s_waitcnt lgkmcnt(11)
	v_fmac_f32_e32 v88, v46, v162
	v_fmac_f32_e32 v90, v47, v163
	v_fmac_f32_e32 v88, v44, v164
	v_fmac_f32_e32 v90, v45, v165
	ds_read_b128 v[162:165], v143 offset:15648
	s_waitcnt lgkmcnt(11)
	v_fmac_f32_e32 v88, v42, v166
	v_fmac_f32_e32 v90, v43, v167
	v_fmac_f32_e32 v88, v40, v168
	v_fmac_f32_e32 v90, v41, v169
	ds_read_b128 v[166:169], v143 offset:15664
	s_waitcnt lgkmcnt(11)
; DI void gdn_g1(const Params& p, int l, int ch, char* smem) {
;     ...
;     for (int cc = 1; cc < 64; ++cc) { float a0 = 0.f, a1 = 0.f;
; #pragma unroll
;       for (int s2 = 0; s2 < cc; ++s2) { if (s2 & 1) a1 += sA[cc * 64 + s2] * sol[s2]; else a0 += sA[cc * 64 + s2] * sol[s2]; }
;       sol[cc] -= a0 + a1; }
	v_fmac_f32_e32 v88, v38, v114
	v_fmac_f32_e32 v90, v39, v115
	v_fmac_f32_e32 v88, v36, v116
	v_fmac_f32_e32 v90, v37, v117
	ds_read_b128 v[114:117], v143 offset:15680
	s_waitcnt lgkmcnt(11)
	v_fmac_f32_e32 v88, v34, v118
	v_fmac_f32_e32 v90, v35, v119
	v_fmac_f32_e32 v88, v32, v120
	v_fmac_f32_e32 v90, v33, v121
	ds_read_b128 v[118:121], v143 offset:15696
	s_waitcnt lgkmcnt(11)
	v_fmac_f32_e32 v88, v30, v122
	v_fmac_f32_e32 v90, v31, v123
	v_fmac_f32_e32 v88, v28, v124
	v_fmac_f32_e32 v90, v29, v125
	ds_read_b128 v[122:125], v143 offset:15712
	s_waitcnt lgkmcnt(11)
	v_fmac_f32_e32 v88, v26, v126
	v_fmac_f32_e32 v90, v27, v127
	v_fmac_f32_e32 v88, v24, v128
	v_fmac_f32_e32 v90, v25, v129
	ds_read_b128 v[126:129], v143 offset:15728
	s_waitcnt lgkmcnt(11)
	v_fmac_f32_e32 v88, v22, v130
	v_fmac_f32_e32 v90, v23, v131
	v_fmac_f32_e32 v88, v20, v132
	v_fmac_f32_e32 v90, v21, v133
	ds_read_b128 v[130:133], v143 offset:15744
	s_waitcnt lgkmcnt(11)
	v_fmac_f32_e32 v88, v18, v134
	v_fmac_f32_e32 v90, v19, v135
	v_fmac_f32_e32 v88, v16, v136
	v_fmac_f32_e32 v90, v17, v137
	ds_read_b128 v[134:137], v143 offset:15760
	s_waitcnt lgkmcnt(11)
	v_fmac_f32_e32 v88, v14, v146
	v_fmac_f32_e32 v90, v15, v147
	v_fmac_f32_e32 v88, v12, v148
	v_fmac_f32_e32 v90, v13, v149
	ds_read_b128 v[146:149], v143 offset:15776
	s_waitcnt lgkmcnt(11)
	v_fmac_f32_e32 v88, v10, v150
	v_fmac_f32_e32 v90, v11, v151
	v_fmac_f32_e32 v88, v8, v152
	v_fmac_f32_e32 v90, v9, v153
	v_add_f32_e32 v84, v88, v90
	v_sub_f32_e32 v6, v6, v84
	ds_read_b128 v[150:153], v143 offset:15792
	s_waitcnt lgkmcnt(11)
	v_fma_f32 v88, v4, v154, 0
	v_fma_f32 v90, v5, v155, 0
	v_fmac_f32_e32 v88, v80, v156
	v_fmac_f32_e32 v90, v81, v157
	ds_read_b128 v[154:157], v143 offset:15808
	s_waitcnt lgkmcnt(11)
	v_fmac_f32_e32 v88, v82, v158
	v_fmac_f32_e32 v90, v83, v159
	v_fmac_f32_e32 v88, v60, v160
	v_fmac_f32_e32 v90, v61, v161
	ds_read_b128 v[158:161], v143 offset:15824
	s_waitcnt lgkmcnt(11)
	v_fmac_f32_e32 v88, v58, v162
	v_fmac_f32_e32 v90, v59, v163
	v_fmac_f32_e32 v88, v56, v164
	v_fmac_f32_e32 v90, v57, v165
	ds_read_b128 v[162:165], v143 offset:15840
	s_waitcnt lgkmcnt(11)
	v_fmac_f32_e32 v88, v54, v166
	v_fmac_f32_e32 v90, v55, v167
	v_fmac_f32_e32 v88, v52, v168
	v_fmac_f32_e32 v90, v53, v169
	ds_read_b32 v166, v143 offset:15856
	s_waitcnt lgkmcnt(11)
	v_fmac_f32_e32 v88, v50, v114
	v_fmac_f32_e32 v90, v51, v115
	v_fmac_f32_e32 v88, v48, v116
	v_fmac_f32_e32 v90, v49, v117
	ds_read_b128 v[114:117], v143 offset:15872
	s_waitcnt lgkmcnt(11)
	v_fmac_f32_e32 v88, v46, v118
	v_fmac_f32_e32 v90, v47, v119
	v_fmac_f32_e32 v88, v44, v120
	v_fmac_f32_e32 v90, v45, v121
	ds_read_b128 v[118:121], v143 offset:15888
	s_waitcnt lgkmcnt(11)
	v_fmac_f32_e32 v88, v42, v122
	v_fmac_f32_e32 v90, v43, v123
	v_fmac_f32_e32 v88, v40, v124
	v_fmac_f32_e32 v90, v41, v125
	ds_read_b128 v[122:125], v143 offset:15904
	s_waitcnt lgkmcnt(11)
	v_fmac_f32_e32 v88, v38, v126
	v_fmac_f32_e32 v90, v39, v127
	v_fmac_f32_e32 v88, v36, v128
	v_fmac_f32_e32 v90, v37, v129
	ds_read_b128 v[126:129], v143 offset:15920
	s_waitcnt lgkmcnt(11)
	v_fmac_f32_e32 v88, v34, v130
	v_fmac_f32_e32 v90, v35, v131
	v_fmac_f32_e32 v88, v32, v132
	v_fmac_f32_e32 v90, v33, v133
	ds_read_b128 v[130:133], v143 offset:15936
	s_waitcnt lgkmcnt(11)
	v_fmac_f32_e32 v88, v30, v134
	v_fmac_f32_e32 v90, v31, v135
	v_fmac_f32_e32 v88, v28, v136
	v_fmac_f32_e32 v90, v29, v137
	ds_read_b128 v[134:137], v143 offset:15952
	s_waitcnt lgkmcnt(11)
	v_fmac_f32_e32 v88, v26, v146
	v_fmac_f32_e32 v90, v27, v147
	v_fmac_f32_e32 v88, v24, v148
	v_fmac_f32_e32 v90, v25, v149
	ds_read_b128 v[146:149], v143 offset:15968
	s_waitcnt lgkmcnt(11)
	v_fmac_f32_e32 v88, v22, v150
	v_fmac_f32_e32 v90, v23, v151
	v_fmac_f32_e32 v88, v20, v152
	v_fmac_f32_e32 v90, v21, v153
	ds_read_b128 v[150:153], v143 offset:15984
	s_waitcnt lgkmcnt(11)
	v_fmac_f32_e32 v88, v18, v154
	v_fmac_f32_e32 v90, v19, v155
	v_fmac_f32_e32 v88, v16, v156
	v_fmac_f32_e32 v90, v17, v157
	ds_read_b128 v[154:157], v143 offset:16000
	s_waitcnt lgkmcnt(11)
	v_fmac_f32_e32 v88, v14, v158
	v_fmac_f32_e32 v90, v15, v159
	v_fmac_f32_e32 v88, v12, v160
	v_fmac_f32_e32 v90, v13, v161
	ds_read_b128 v[158:161], v143 offset:16016
	s_waitcnt lgkmcnt(11)
	v_fmac_f32_e32 v88, v10, v162
	v_fmac_f32_e32 v90, v11, v163
	v_fmac_f32_e32 v88, v8, v164
	v_fmac_f32_e32 v90, v9, v165
	ds_read_b128 v[162:165], v143 offset:16032
	s_waitcnt lgkmcnt(11)
	v_fmac_f32_e32 v88, v6, v166
	v_add_f32_e32 v84, v90, v88
	v_sub_f32_e32 v7, v7, v84
	ds_read_b128 v[166:169], v143 offset:16048
	s_waitcnt lgkmcnt(11)
	v_fma_f32 v88, v4, v114, 0
	v_fma_f32 v90, v5, v115, 0
	v_fmac_f32_e32 v88, v80, v116
	v_fmac_f32_e32 v90, v81, v117
	ds_read_b128 v[114:117], v143 offset:16064
	s_waitcnt lgkmcnt(11)
	v_fmac_f32_e32 v88, v82, v118
	v_fmac_f32_e32 v90, v83, v119
	v_fmac_f32_e32 v88, v60, v120
	v_fmac_f32_e32 v90, v61, v121
	ds_read_b128 v[118:121], v143 offset:16080
	s_waitcnt lgkmcnt(11)
	v_fmac_f32_e32 v88, v58, v122
	v_fmac_f32_e32 v90, v59, v123
	v_fmac_f32_e32 v88, v56, v124
	v_fmac_f32_e32 v90, v57, v125
	ds_read_b128 v[122:125], v143 offset:16096
	s_waitcnt lgkmcnt(11)
	v_fmac_f32_e32 v88, v54, v126
	v_fmac_f32_e32 v90, v55, v127
	v_fmac_f32_e32 v88, v52, v128
	v_fmac_f32_e32 v90, v53, v129
	ds_read_b64 v[126:127], v143 offset:16112
	s_waitcnt lgkmcnt(11)
	v_fmac_f32_e32 v88, v50, v130
	v_fmac_f32_e32 v90, v51, v131
	v_fmac_f32_e32 v88, v48, v132
	v_fmac_f32_e32 v90, v49, v133
	ds_read_b128 v[130:133], v143 offset:16128
	s_waitcnt lgkmcnt(11)
	v_fmac_f32_e32 v88, v46, v134
	v_fmac_f32_e32 v90, v47, v135
	v_fmac_f32_e32 v88, v44, v136
	v_fmac_f32_e32 v90, v45, v137
	ds_read_b128 v[134:137], v143 offset:16144
	s_waitcnt lgkmcnt(11)
; DI void gdn_g1(const Params& p, int l, int ch, char* smem) {
;     ...
;     for (int cc = 1; cc < 64; ++cc) { float a0 = 0.f, a1 = 0.f;
; #pragma unroll
;       for (int s2 = 0; s2 < cc; ++s2) { if (s2 & 1) a1 += sA[cc * 64 + s2] * sol[s2]; else a0 += sA[cc * 64 + s2] * sol[s2]; }
;       sol[cc] -= a0 + a1; }
; #pragma unroll
;     for (int cc = 1; cc < 64; ++cc) sR[cc * 129 + tid] = sol[cc];
	v_fmac_f32_e32 v88, v42, v146
	v_fmac_f32_e32 v90, v43, v147
	v_fmac_f32_e32 v88, v40, v148
	v_fmac_f32_e32 v90, v41, v149
	ds_read_b128 v[146:149], v143 offset:16160
	s_waitcnt lgkmcnt(11)
	v_fmac_f32_e32 v88, v38, v150
	v_fmac_f32_e32 v90, v39, v151
	v_fmac_f32_e32 v88, v36, v152
	v_fmac_f32_e32 v90, v37, v153
	ds_read_b128 v[150:153], v143 offset:16176
	s_waitcnt lgkmcnt(11)
	v_fmac_f32_e32 v88, v34, v154
	v_fmac_f32_e32 v90, v35, v155
	v_fmac_f32_e32 v88, v32, v156
	v_fmac_f32_e32 v90, v33, v157
	ds_read_b128 v[154:157], v143 offset:16192
	s_waitcnt lgkmcnt(11)
	v_fmac_f32_e32 v88, v30, v158
	v_fmac_f32_e32 v90, v31, v159
	v_fmac_f32_e32 v88, v28, v160
	v_fmac_f32_e32 v90, v29, v161
	ds_read_b128 v[158:161], v143 offset:16208
	s_waitcnt lgkmcnt(11)
	v_fmac_f32_e32 v88, v26, v162
	v_fmac_f32_e32 v90, v27, v163
	v_fmac_f32_e32 v88, v24, v164
	v_fmac_f32_e32 v90, v25, v165
	ds_read_b128 v[162:165], v143 offset:16224
	s_waitcnt lgkmcnt(11)
	v_fmac_f32_e32 v88, v22, v166
	v_fmac_f32_e32 v90, v23, v167
	v_fmac_f32_e32 v88, v20, v168
	v_fmac_f32_e32 v90, v21, v169
	ds_read_b128 v[166:169], v143 offset:16240
	s_waitcnt lgkmcnt(11)
	v_fmac_f32_e32 v88, v18, v114
	v_fmac_f32_e32 v90, v19, v115
	v_fmac_f32_e32 v88, v16, v116
	v_fmac_f32_e32 v90, v17, v117
	ds_read_b128 v[114:117], v143 offset:16256
	s_waitcnt lgkmcnt(11)
	v_fmac_f32_e32 v88, v14, v118
	v_fmac_f32_e32 v90, v15, v119
	v_fmac_f32_e32 v88, v12, v120
	v_fmac_f32_e32 v90, v13, v121
	ds_read_b128 v[118:121], v143 offset:16272
	s_waitcnt lgkmcnt(11)
	v_fmac_f32_e32 v88, v10, v122
	v_fmac_f32_e32 v90, v11, v123
	v_fmac_f32_e32 v88, v8, v124
	v_fmac_f32_e32 v90, v9, v125
	ds_read_b128 v[122:125], v143 offset:16288
	s_waitcnt lgkmcnt(11)
	v_fmac_f32_e32 v88, v6, v126
	v_fmac_f32_e32 v90, v7, v127
	v_add_f32_e32 v84, v88, v90
	v_sub_f32_e32 v2, v2, v84
	ds_read_b128 v[126:129], v143 offset:16304
	s_waitcnt lgkmcnt(11)
	v_fma_f32 v4, v4, v130, 0
	v_fma_f32 v88, v5, v131, 0
	v_fmac_f32_e32 v4, v80, v132
	v_fmac_f32_e32 v88, v81, v133
	ds_read_b128 v[130:133], v143 offset:16320
	s_waitcnt lgkmcnt(11)
	v_fmac_f32_e32 v4, v82, v134
	v_fmac_f32_e32 v88, v83, v135
	v_fmac_f32_e32 v4, v60, v136
	v_fmac_f32_e32 v88, v61, v137
	ds_read_b128 v[134:137], v143 offset:16336
	s_waitcnt lgkmcnt(11)
	v_fmac_f32_e32 v4, v58, v146
	v_fmac_f32_e32 v88, v59, v147
	v_fmac_f32_e32 v4, v56, v148
	v_fmac_f32_e32 v88, v57, v149
	ds_read_b128 v[146:149], v143 offset:16352
	s_waitcnt lgkmcnt(11)
	v_fmac_f32_e32 v4, v54, v150
	v_fmac_f32_e32 v88, v55, v151
	v_fmac_f32_e32 v4, v52, v152
	v_fmac_f32_e32 v88, v53, v153
	ds_read_b96 v[150:152], v143 offset:16368
	s_waitcnt lgkmcnt(11)
	v_fmac_f32_e32 v4, v50, v154
	v_fmac_f32_e32 v88, v51, v155
	v_fmac_f32_e32 v4, v48, v156
	v_fmac_f32_e32 v88, v49, v157
	s_waitcnt lgkmcnt(10)
	v_fmac_f32_e32 v4, v46, v158
	v_fmac_f32_e32 v88, v47, v159
	v_fmac_f32_e32 v4, v44, v160
	v_fmac_f32_e32 v88, v45, v161
	s_waitcnt lgkmcnt(9)
	v_fmac_f32_e32 v4, v42, v162
	v_fmac_f32_e32 v88, v43, v163
	v_fmac_f32_e32 v4, v40, v164
	v_fmac_f32_e32 v88, v41, v165
	s_waitcnt lgkmcnt(8)
	v_fmac_f32_e32 v4, v38, v166
	v_fmac_f32_e32 v88, v39, v167
	v_fmac_f32_e32 v4, v36, v168
	v_fmac_f32_e32 v88, v37, v169
	s_waitcnt lgkmcnt(7)
	v_fmac_f32_e32 v4, v34, v114
	v_fmac_f32_e32 v88, v35, v115
	v_fmac_f32_e32 v4, v32, v116
	v_fmac_f32_e32 v88, v33, v117
	s_waitcnt lgkmcnt(6)
	v_fmac_f32_e32 v4, v30, v118
	v_fmac_f32_e32 v88, v31, v119
	v_fmac_f32_e32 v4, v28, v120
	v_fmac_f32_e32 v88, v29, v121
	s_waitcnt lgkmcnt(5)
	v_fmac_f32_e32 v4, v26, v122
	v_fmac_f32_e32 v88, v27, v123
	v_fmac_f32_e32 v4, v24, v124
	v_fmac_f32_e32 v88, v25, v125
	s_waitcnt lgkmcnt(4)
	v_fmac_f32_e32 v4, v22, v126
	v_fmac_f32_e32 v88, v23, v127
	v_fmac_f32_e32 v4, v20, v128
	v_fmac_f32_e32 v88, v21, v129
	s_waitcnt lgkmcnt(3)
	v_fmac_f32_e32 v4, v18, v130
	v_fmac_f32_e32 v88, v19, v131
	v_fmac_f32_e32 v4, v16, v132
	v_fmac_f32_e32 v88, v17, v133
	s_waitcnt lgkmcnt(2)
	v_fmac_f32_e32 v4, v14, v134
	v_fmac_f32_e32 v88, v15, v135
	v_fmac_f32_e32 v4, v12, v136
	v_fmac_f32_e32 v88, v13, v137
	s_waitcnt lgkmcnt(1)
	v_fmac_f32_e32 v4, v10, v146
	v_fmac_f32_e32 v88, v11, v147
	v_fmac_f32_e32 v4, v8, v148
	v_fmac_f32_e32 v88, v9, v149
	s_waitcnt lgkmcnt(0)
	v_fmac_f32_e32 v4, v6, v150
	v_fmac_f32_e32 v88, v7, v151
	v_fmac_f32_e32 v4, v2, v152
	v_add_f32_e32 v4, v88, v4
	v_sub_f32_e32 v3, v3, v4
	v_add_u32_e32 v4, 0x4200, v79
	ds_write2_b32 v4, v5, v80 offset0:1 offset1:130
	v_add_u32_e32 v4, 0x4600, v79
	ds_write2_b32 v4, v81, v82 offset0:3 offset1:132
	v_add_u32_e32 v4, 0x4a00, v79
	ds_write2_b32 v4, v83, v60 offset0:5 offset1:134
	v_add_u32_e32 v4, 0x4e00, v79
	ds_write2_b32 v4, v61, v58 offset0:7 offset1:136
	v_add_u32_e32 v4, 0x5200, v79
	ds_write2_b32 v4, v59, v56 offset0:9 offset1:138
	v_add_u32_e32 v4, 0x5600, v79
	ds_write2_b32 v4, v57, v54 offset0:11 offset1:140
	v_add_u32_e32 v4, 0x5a00, v79
	ds_write2_b32 v4, v55, v52 offset0:13 offset1:142
	v_add_u32_e32 v4, 0x5e00, v79
	ds_write2_b32 v4, v53, v50 offset0:15 offset1:144
	v_add_u32_e32 v4, 0x6200, v79
	ds_write2_b32 v4, v51, v48 offset0:17 offset1:146
	v_add_u32_e32 v4, 0x6600, v79
	ds_write2_b32 v4, v49, v46 offset0:19 offset1:148
	v_add_u32_e32 v4, 0x6a00, v79
	ds_write2_b32 v4, v47, v44 offset0:21 offset1:150
	v_add_u32_e32 v4, 0x6e00, v79
	ds_write2_b32 v4, v45, v42 offset0:23 offset1:152
	v_add_u32_e32 v4, 0x7200, v79
	ds_write2_b32 v4, v43, v40 offset0:25 offset1:154
	v_add_u32_e32 v4, 0x7600, v79
	ds_write2_b32 v4, v41, v38 offset0:27 offset1:156
	v_add_u32_e32 v4, 0x7a00, v79
	ds_write2_b32 v4, v39, v36 offset0:29 offset1:158
	v_add_u32_e32 v4, 0x7e00, v79
	ds_write2_b32 v4, v37, v34 offset0:31 offset1:160
	v_add_u32_e32 v4, 0x8200, v79
	ds_write2_b32 v4, v35, v32 offset0:33 offset1:162
	v_add_u32_e32 v4, 0x8600, v79
	ds_write2_b32 v4, v33, v30 offset0:35 offset1:164
	v_add_u32_e32 v4, 0x8a00, v79
	ds_write2_b32 v4, v31, v28 offset0:37 offset1:166
	v_add_u32_e32 v4, 0x8e00, v79
	ds_write2_b32 v4, v29, v26 offset0:39 offset1:168
	v_add_u32_e32 v4, 0x9200, v79
	ds_write2_b32 v4, v27, v24 offset0:41 offset1:170
	v_add_u32_e32 v4, 0x9600, v79
	ds_write2_b32 v4, v25, v22 offset0:43 offset1:172
	v_add_u32_e32 v4, 0x9a00, v79
	ds_write2_b32 v4, v23, v20 offset0:45 offset1:174
	v_add_u32_e32 v4, 0x9e00, v79
	ds_write2_b32 v4, v21, v18 offset0:47 offset1:176
	v_add_u32_e32 v4, 0xa200, v79
	ds_write2_b32 v4, v19, v16 offset0:49 offset1:178
	v_add_u32_e32 v4, 0xa600, v79
	ds_write2_b32 v4, v17, v14 offset0:51 offset1:180
	v_add_u32_e32 v4, 0xaa00, v79
	ds_write2_b32 v4, v15, v12 offset0:53 offset1:182
	v_add_u32_e32 v4, 0xae00, v79
	ds_write2_b32 v4, v13, v10 offset0:55 offset1:184
	v_add_u32_e32 v4, 0xb200, v79
	ds_write2_b32 v4, v11, v8 offset0:57 offset1:186
	v_add_u32_e32 v4, 0xb600, v79
	ds_write2_b32 v4, v9, v6 offset0:59 offset1:188
	v_add_u32_e32 v4, 0xba00, v79
	ds_write2_b32 v4, v7, v2 offset0:61 offset1:190
	ds_write_b32 v79, v3 offset:48892
